# P5 tail tiles: parts 0/1 on two workgroups concurrently with flag-ordered RMW epilogue, + P9 K-split exchange
# speedup vs baseline: 1.0141x; 1.0014x over previous
; #define LAS __attribute__((address_space(3)))
;     __device__ __forceinline__ bool next(int i, Unit& u) const {
;         const int r = i / np; u.part = i - r * np;
;         long L = (long)r * G + c;
;         if (L >= split_from) { const long Ls = L - split_from; if (Ls >= 2L * (nwg - split_from)) return false; L = split_from + (Ls >> 1); u.part = 1 + (int)(Ls & 1); }
;         if (L >= nwg) return false;
;         int wgid = (int)L; { const int q = nwg / NXCD, rr = nwg % NXCD, xcd = wgid % NXCD, off = wgid / NXCD; wgid = (xcd < rr ? xcd * (q + 1) : rr * (q + 1) + (xcd - rr) * q) + off; }
; __global__ void __launch_bounds__(512, 2) mega_fwd(Args a) {
;     ...
;               {
;                   Unit u; const int k = tq >> 8, row = tq & 255;
;                   if (S.next(2 * k, u)) {
;                       const f32x4* q = (const f32x4*)(ssq + (size_t)(u.pm * 256 + row) * NH);
;                       float r[4];
; #pragma unroll
;                       for (int gq = 0; gq < 4; ++gq) { const f32x4 x0 = q[2 * gq], x1 = q[2 * gq + 1]; r[gq] = rsqrtf(((x0[0] + x0[1]) + (x0[2] + x0[3]) + (x1[0] + x1[1]) + (x1[2] + x1[3])) * (1.f / 512.f) + EPS); }
;                       *(LAS f32x4*)(lds + pg8::STAGE_BYTES + (k * 256 + row) * 16) = (f32x4){r[0] / r[1], r[1] / r[2], r[2] / r[3], r[3]};
;                   }
;                   __syncthreads();
;               }
.LBB0_642:
	s_or_b64 exec, exec, s[4:5]
	v_readlane_b32 s2, v255, 32
	s_lshr_b32 s10, s2, 6
	v_readlane_b32 s2, v254, 38
	v_readlane_b32 s3, v254, 39
	v_mov_b32_e32 v0, v166
	s_waitcnt lgkmcnt(0)
	v_mov_b64_e32 v[2:3], s[2:3]
	v_readlane_b32 s2, v252, 0
	s_barrier
	s_mov_b32 s100, 0
	s_mov_b32 s101, 0
	v_readlane_b32 s3, v252, 1
	v_ashrrev_i32_e32 v4, 8, v0
	v_mad_i64_i32 v[2:3], s[2:3], v4, s2, v[2:3]
	s_sub_i32 s6, s10, 0x100
	s_lshl_b32 s6, s6, 1
	v_subrev_u32_e32 v5, 0x100, v2
	v_lshrrev_b32_e32 v6, 1, v5
	v_add_u32_e32 v6, 0x100, v6
	v_mov_b32_e32 v7, 0x7fff
	v_cmp_gt_u32_e32 vcc, s6, v5
	s_nop 1
	v_cndmask_b32_e32 v6, v7, v6, vcc
	v_cmp_lt_i32_e32 vcc, 0xff, v2
	s_nop 1
	v_cndmask_b32_e32 v2, v2, v6, vcc
	v_cmp_le_i64_e32 vcc, s[10:11], v[2:3]
	v_cmp_gt_i64_e64 s[4:5], s[10:11], v[2:3]
	s_and_saveexec_b64 s[6:7], s[4:5]
	s_cbranch_execz .LBB0_644
	v_ashrrev_i32_e32 v3, 31, v2
	v_lshrrev_b32_e32 v3, 29, v3
	v_add_u32_e32 v3, v2, v3
	v_ashrrev_i32_e32 v4, 3, v3
	v_and_b32_e32 v3, -8, v3
	v_readlane_b32 s2, v255, 32
	v_sub_u32_e32 v2, v2, v3
	s_lshr_b32 s2, s2, 9
	v_lshrrev_b32_e32 v3, 31, v2
	v_or_b32_e32 v3, s2, v3
	v_mul_lo_u32 v2, v2, v3
	v_add_u32_e32 v2, v2, v4
	v_ashrrev_i32_e32 v3, 31, v2
	v_lshrrev_b32_e32 v3, 27, v3
	v_add_u32_e32 v3, v2, v3
	v_ashrrev_i32_e32 v4, 5, v3
	v_lshlrev_b32_e32 v4, 3, v4
	v_readlane_b32 s2, v255, 35
	v_and_b32_e32 v3, 0xffffffe0, v3
	v_sub_u32_e32 v2, v2, v3
	v_sub_u32_e32 v5, s2, v4
	v_min_i32_e32 v5, 8, v5
	v_sub_u32_e32 v6, 0, v5
	v_max_i32_e32 v5, v5, v6
	v_cvt_f32_u32_e32 v6, v5
	v_sub_u32_e32 v7, 0, v2
	v_ashrrev_i32_e32 v3, 31, v2
	v_max_i32_e32 v2, v2, v7
	v_rcp_iflag_f32_e32 v6, v6
	v_sub_u32_e32 v7, 0, v5
	v_mul_f32_e32 v6, 0x4f7ffffe, v6
	v_cvt_u32_f32_e32 v6, v6
	v_mul_lo_u32 v7, v7, v6
	v_mul_hi_u32 v7, v6, v7
	v_add_u32_e32 v6, v6, v7
	v_mul_hi_u32 v6, v2, v6
	v_mul_lo_u32 v6, v6, v5
	v_sub_u32_e32 v2, v2, v6
	v_sub_u32_e32 v6, v2, v5
	v_cmp_ge_u32_e64 s[4:5], v2, v5
	s_nop 1
	v_cndmask_b32_e64 v2, v2, v6, s[4:5]
	v_sub_u32_e32 v6, v2, v5
	v_cmp_ge_u32_e64 s[4:5], v2, v5
	s_nop 1
	v_cndmask_b32_e64 v2, v2, v6, s[4:5]
	v_xor_b32_e32 v2, v2, v3
	v_sub_u32_e32 v2, v2, v3
	v_add_u32_e32 v214, v4, v2

;     __device__ __forceinline__ const char* Ap(int part) const { return (const char*)A0 + (long)(part == 1) * ((const char*)A1 - (const char*)A0) + (long)(part == 2) * ((const char*)A2 - (const char*)A0); }
;     __device__ __forceinline__ const char* Bp(int part) const { return (const char*)B0 + (long)(part == 1) * ((const char*)B1 - (const char*)B0) + (long)(part == 2) * ((const char*)B2 - (const char*)B0); }
;     __device__ __forceinline__ bool next(int i, Unit& u) const {
;         const int r = i / np; u.part = i - r * np;
;         long L = (long)r * G + c;
;         if (L >= split_from) { const long Ls = L - split_from; if (Ls >= 2L * (nwg - split_from)) return false; L = split_from + (Ls >> 1); u.part = 1 + (int)(Ls & 1); }
;         if (L >= nwg) return false;
;         int wgid = (int)L; { const int q = nwg / NXCD, rr = nwg % NXCD, xcd = wgid % NXCD, off = wgid / NXCD; wgid = (xcd < rr ? xcd * (q + 1) : rr * (q + 1) + (xcd - rr) * q) + off; }
;         const int nig = WGM * nN, gid = wgid / nig, fm = gid * WGM, gsz = (nM - fm) < WGM ? (nM - fm) : WGM;
;         u.pm = fm + ((wgid % nig) % gsz); u.pn = (wgid % nig) / gsz; return true;
;     }
; template <class Epi, bool GS = false>
; __device__ __forceinline__ void gemm_phase(LAS unsigned char* lds, const Gemm g, const StaticOrder& S, const Epi& E, const int tid) {
;     ...
;     for (;;) {
;         const bool has_next = S.next(ui + 1, nxt);
;         const char* nA = has_next ? g.Ap(nxt.part) + (size_t)nxt.pm * tstepA : cA; const char* nB = has_next ? g.Bp(nxt.part) + (size_t)nxt.pn * tstepB : cB;
;         const int nt = g.Kp(cur.part) / BK;
;         const int seg = (GS && cur.part == 0) ? 8 : nt;
.LBB0_655:
	s_mov_b32 s100, s101
	s_andn2_b64 vcc, exec, s[4:5]
	s_mov_b32 s16, s58
	s_mov_b32 s59, s56
	s_mov_b32 s60, s57
	s_mov_b64 s[20:21], s[48:49]
	s_mov_b64 s[8:9], s[46:47]
	s_mov_b32 s22, s55
	s_cbranch_vccz .LBB0_719
.LBB0_656:
	s_add_i32 s55, s22, 1
	v_readlane_b32 s14, v252, 0
	s_lshr_b32 s4, s55, 1
	v_readlane_b32 s15, v252, 1
	s_mul_hi_i32 s5, s4, s14
	s_mul_i32 s4, s4, s14
	v_readlane_b32 s14, v254, 38
	v_readlane_b32 s15, v254, 39
	s_add_u32 s14, s4, s14
	s_addc_u32 s15, s5, s15
	s_mov_b32 s101, 0
	s_cmp_lt_u32 s14, 0x100
	s_cbranch_scc1 .Lpp5_ns
	s_sub_i32 s17, s14, 0x100
	s_lshr_b32 s23, s17, 1
	s_add_i32 s14, s23, 0x100
	s_and_b32 s101, s17, 1
	s_add_i32 s101, s101, 1
	s_sub_i32 s23, s10, 0x100
	s_lshl_b32 s23, s23, 1
	s_cmp_lt_u32 s17, s23
	s_cselect_b32 s14, s14, 0x7fff
	s_bitcmp1_b32 s55, 0
	s_cselect_b32 s14, 0x7fff, s14
.Lpp5_ns:
	v_mov_b64_e32 v[2:3], s[10:11]
	v_cmp_ge_i64_e32 vcc, s[14:15], v[2:3]
	v_cmp_lt_i64_e64 s[4:5], s[14:15], v[2:3]
	s_cbranch_vccnz .LBB0_658
	s_ashr_i32 s15, s14, 31
	s_lshr_b32 s15, s15, 29
	s_add_i32 s15, s14, s15
	s_ashr_i32 s17, s15, 3
	s_and_b32 s15, s15, -8
	s_sub_i32 s14, s14, s15
	s_lshr_b32 s15, s14, 31
	s_or_b32 s15, s54, s15
	s_mul_i32 s14, s15, s14
	s_add_i32 s14, s14, s17
	s_ashr_i32 s15, s14, 31
	s_lshr_b32 s15, s15, 27
	s_add_i32 s15, s14, s15
	s_ashr_i32 s17, s15, 5
	s_lshl_b32 s17, s17, 3
	v_readlane_b32 s23, v255, 35
	s_sub_i32 s23, s23, s17
	s_min_i32 s23, s23, 8
	s_abs_i32 s40, s23
	v_cvt_f32_u32_e32 v0, s40
	s_sub_i32 s42, 0, s40
	s_andn2_b32 s15, s15, 31
	s_sub_i32 s14, s14, s15
	v_rcp_iflag_f32_e32 v0, v0
	s_abs_i32 s15, s14
	s_xor_b32 s41, s14, s23
	s_ashr_i32 s41, s41, 31
	v_mul_f32_e32 v0, 0x4f7ffffe, v0
	v_cvt_u32_f32_e32 v0, v0
	s_nop 0
	v_readfirstlane_b32 s43, v0
	s_mul_i32 s42, s42, s43
	s_mul_hi_u32 s42, s43, s42
	s_add_i32 s43, s43, s42
	s_mul_hi_u32 s42, s15, s43
	s_mul_i32 s43, s42, s40
	s_sub_i32 s15, s15, s43
	s_add_i32 s46, s42, 1
	s_sub_i32 s43, s15, s40
	s_cmp_ge_u32 s15, s40
	s_cselect_b32 s42, s46, s42
	s_cselect_b32 s15, s43, s15
	s_add_i32 s43, s42, 1
	s_cmp_ge_u32 s15, s40
	s_cselect_b32 s15, s43, s42
	s_xor_b32 s15, s15, s41
	s_sub_i32 s56, s15, s41
	s_mul_i32 s15, s56, s23
	s_sub_i32 s14, s14, s15
	s_add_i32 s57, s14, s17
.LBB0_658:
	s_nop 0
	v_cndmask_b32_e64 v0, 0, 1, s[4:5]
	s_and_b32 s58, s55, 1
	s_cmp_eq_u32 s101, 0
	s_cbranch_scc1 .Lpp5_p
	s_add_i32 s58, s101, -1
.Lpp5_p:
	v_cmp_ne_u32_e64 s[40:41], 1, v0
	s_andn2_b64 vcc, exec, s[4:5]
	s_mov_b64 s[46:47], s[8:9]
	s_cbranch_vccnz .LBB0_660
	s_cmp_eq_u32 s58, 0
	s_cselect_b32 s4, 0, 0x2800
	s_add_u32 s4, s18, s4
	s_addc_u32 s5, s19, 0
	s_mul_i32 s15, s57, 0x460000
	s_mul_hi_i32 s14, s57, 0x460000
	s_add_u32 s46, s4, s15
	s_addc_u32 s47, s5, s14

;     __device__ __forceinline__ void operator()(const f32x4 (&acc)[2][2][4][2], const Unit& u, int wr, int wc, int fr, int fq) const {
;         const int row0 = u.pm * BM + wr * 64 + fr, col0 = u.pn * BM + wc * 32 + 8 * fq;
;         const int gbase = u.part == 0 ? C_GS : C_GA;
; #pragma unroll
;         for (int ai = 0; ai < 2; ++ai) {
; #pragma unroll
;             for (int mp = 0; mp < 2; ++mp) {
;             u32x4 gw[2][2], pw[2][2];
.LBB0_684:
	s_cmp_eq_u32 s100, 2
	s_cbranch_scc0 .Lpp5_nw
	v_readfirstlane_b32 s20, v166
	s_nop 0
	s_cmp_lt_u32 s20, 64
	s_cbranch_scc0 .Lpp5_wb
	v_readlane_b32 s21, v252, 2
	s_lshr_b32 s21, s21, 9
	s_lshl_b32 s21, s21, 2
	s_addk_i32 s21, 0x3700
	v_mov_b32_e32 v188, s21
	s_add_u32 s4, s26, 0x1d780000
	s_addc_u32 s5, s27, 0
	s_mov_b32 s28, 0
.Lpp5_poll:
	global_load_dword v189, v188, s[4:5] sc0 sc1
	s_waitcnt vmcnt(0)
	v_readfirstlane_b32 s29, v189
	s_add_i32 s28, s28, 1
	s_cmp_eq_u32 s29, 1
	s_cbranch_scc1 .Lpp5_got
	s_sleep 1
	s_cmp_lt_u32 s28, 0x8000
	s_cbranch_scc1 .Lpp5_poll
.Lpp5_got:
	global_store_dword v188, v1, s[4:5] sc0 sc1
	s_waitcnt vmcnt(0)

; __device__ __forceinline__ unsigned pk2(float lo, float hi) { unsigned r; asm("v_cvt_pk_bf16_f32 %0, %1, %2" : "=v"(r) : "v"(lo), "v"(hi)); return r; }
; __device__ __forceinline__ float bflo(unsigned w) { return __uint_as_float(w << 16); }
; __device__ __forceinline__ float bfhi(unsigned w) { return __uint_as_float(w & 0xffff0000u); }
; __device__ __forceinline__ float sigmoidf_(float x) { return __builtin_amdgcn_rcpf(1.f + __expf(-x)); }
;     __device__ __forceinline__ void operator()(const f32x4 (&acc)[2][2][4][2], const Unit& u, int wr, int wc, int fr, int fq) const {
;     ...
;             u32x4 gw[2][2], pw[2][2];
; #pragma unroll
;             for (int mm = 0; mm < 2; ++mm) { const int row = row0 + ai * HALF + (2 * mp + mm) * 16;
; #pragma unroll
;                 for (int bj = 0; bj < 2; ++bj) { const int col = col0 + bj * HALF;
;                     gw[mm][bj] = *(const u32x4*)(proj + (size_t)row * PN + gbase + col);
;                     pw[mm][bj] = u.part == 1 ? *(const u32x4*)(mix + (size_t)row * DM + col) : (u32x4){0u, 0u, 0u, 0u}; } }
; #pragma unroll
;             for (int mm = 0; mm < 2; ++mm) { const int m = 2 * mp + mm; const int row = row0 + ai * HALF + m * 16;
; #pragma unroll
;                 for (int bj = 0; bj < 2; ++bj) { const int col = col0 + bj * HALF;
;                     const u32x4 g = gw[mm][bj], p = pw[mm][bj];
;                     const f32x4 v0 = acc[ai][bj][m][0], v1 = acc[ai][bj][m][1];
;                     float r[8];
;                     r[0] = sigmoidf_(bflo(g.x)) * v0[0] + bflo(p.x); r[1] = sigmoidf_(bfhi(g.x)) * v0[1] + bfhi(p.x); r[2] = sigmoidf_(bflo(g.y)) * v0[2] + bflo(p.y); r[3] = sigmoidf_(bfhi(g.y)) * v0[3] + bfhi(p.y);
;                     r[4] = sigmoidf_(bflo(g.z)) * v1[0] + bflo(p.z); r[5] = sigmoidf_(bfhi(g.z)) * v1[1] + bfhi(p.z); r[6] = sigmoidf_(bflo(g.w)) * v1[2] + bflo(p.w); r[7] = sigmoidf_(bfhi(g.w)) * v1[3] + bfhi(p.w);
;                     u32x4 w; w.x = pk2(r[0], r[1]); w.y = pk2(r[2], r[3]); w.z = pk2(r[4], r[5]); w.w = pk2(r[6], r[7]);
;                     *(u32x4*)(mix + (size_t)row * DM + col) = w; } }
.Lpp5_nw:
	s_and_b64 s[4:5], s[16:17], exec
	s_movk_i32 s4, 0x3400
	s_cselect_b32 s4, s4, 0x3c00
	s_add_u32 s4, s18, s4
	s_addc_u32 s5, s19, 0
	v_lshl_add_u32 v188, s60, 8, v169
	v_lshl_or_b32 v2, s59, 8, v217
	v_mov_b64_e32 v[120:121], s[4:5]
	v_mad_i64_i32 v[120:121], s[8:9], v188, s33, v[120:121]
	v_ashrrev_i32_e32 v3, 31, v2
	v_lshl_add_u64 v[120:121], v[2:3], 1, v[120:121]
	global_load_dwordx4 v[162:165], v[120:121], off
	v_ashrrev_i32_e32 v189, 31, v188
	v_lshlrev_b64 v[134:135], 11, v[188:189]
	v_lshl_add_u64 v[192:193], s[12:13], 0, v[134:135]
	v_cndmask_b32_e64 v0, 0, 1, s[14:15]
	v_mov_b32_e32 v142, 0
	v_cmp_ne_u32_e64 s[42:43], 1, v0
	s_andn2_b64 vcc, exec, s[14:15]
	v_lshl_add_u64 v[134:135], v[2:3], 1, v[192:193]
	v_mov_b32_e32 v158, 0
	v_mov_b32_e32 v159, 0
	v_mov_b32_e32 v160, 0
	v_mov_b32_e32 v161, 0
	s_cbranch_vccnz .LBB0_686
	global_load_dwordx4 v[158:161], v[134:135], off sc0 sc1
.LBB0_686:
	global_load_dwordx4 v[154:157], v[120:121], off offset:256
	s_and_b64 vcc, exec, s[42:43]
	v_mov_b32_e32 v150, 0
	v_mov_b32_e32 v151, 0
	v_mov_b32_e32 v152, 0
	v_mov_b32_e32 v153, 0
	s_cbranch_vccnz .LBB0_688
	global_load_dwordx4 v[150:153], v[134:135], off offset:256 sc0 sc1
.LBB0_688:
	v_or_b32_e32 v134, 16, v188
	v_mov_b64_e32 v[120:121], s[4:5]
	v_mad_i64_i32 v[120:121], s[8:9], v134, s33, v[120:121]
	v_lshl_add_u64 v[120:121], v[2:3], 1, v[120:121]
	global_load_dwordx4 v[146:149], v[120:121], off
	v_ashrrev_i32_e32 v135, 31, v134
	v_lshlrev_b64 v[134:135], 11, v[134:135]
	v_lshl_add_u64 v[190:191], s[12:13], 0, v[134:135]
	s_and_b64 vcc, exec, s[42:43]
	v_lshl_add_u64 v[194:195], v[2:3], 1, v[190:191]
	v_mov_b32_e32 v143, 0
	v_mov_b32_e32 v144, 0
	v_mov_b32_e32 v145, 0
	s_cbranch_vccnz .LBB0_690
	global_load_dwordx4 v[142:145], v[194:195], off sc0 sc1
.LBB0_690:
	global_load_dwordx4 v[138:141], v[120:121], off offset:256
	v_mov_b32_e32 v120, 0
	s_and_b64 vcc, exec, s[42:43]
	v_mov_b32_e32 v134, 0
	v_mov_b32_e32 v135, 0
	v_mov_b32_e32 v136, 0
	v_mov_b32_e32 v137, 0
	s_cbranch_vccnz .LBB0_692
	global_load_dwordx4 v[134:137], v[194:195], off offset:256 sc0 sc1
.LBB0_692:
	s_waitcnt vmcnt(0)
	v_lshlrev_b32_e32 v0, 16, v162
	v_mul_f32_e32 v0, 0xbfb8aa3b, v0
	v_exp_f32_e32 v0, v0
	v_lshlrev_b32_e32 v121, 16, v158
	s_and_b64 vcc, exec, s[42:43]
	v_add_f32_e32 v0, 1.0, v0
	v_rcp_f32_e32 v0, v0
	s_nop 0
	v_fmac_f32_e32 v121, v130, v0
	v_and_b32_e32 v0, 0xffff0000, v162
	v_mul_f32_e32 v0, 0xbfb8aa3b, v0
	v_exp_f32_e32 v0, v0
	v_and_b32_e32 v130, 0xffff0000, v158
	v_and_b32_e32 v158, 0xffff0000, v160
	v_add_f32_e32 v0, 1.0, v0
	v_rcp_f32_e32 v0, v0
	s_nop 0
	v_fmac_f32_e32 v130, v131, v0
	v_lshlrev_b32_e32 v0, 16, v163
	v_mul_f32_e32 v0, 0xbfb8aa3b, v0
	v_exp_f32_e32 v0, v0
	v_lshlrev_b32_e32 v131, 16, v159
	v_add_f32_e32 v0, 1.0, v0
	v_rcp_f32_e32 v0, v0
	s_nop 0
	v_fmac_f32_e32 v131, v132, v0
	v_and_b32_e32 v0, 0xffff0000, v163
	v_mul_f32_e32 v0, 0xbfb8aa3b, v0
	v_exp_f32_e32 v0, v0
	v_and_b32_e32 v132, 0xffff0000, v159
	v_lshlrev_b32_e32 v159, 16, v161
	v_add_f32_e32 v0, 1.0, v0
	v_rcp_f32_e32 v0, v0
	s_nop 0
	v_fmac_f32_e32 v132, v133, v0
	v_lshlrev_b32_e32 v0, 16, v164
	v_mul_f32_e32 v0, 0xbfb8aa3b, v0
	v_exp_f32_e32 v0, v0
	v_lshlrev_b32_e32 v133, 16, v160
	v_and_b32_e32 v160, 0xffff0000, v161
	v_add_f32_e32 v0, 1.0, v0
	v_rcp_f32_e32 v0, v0
	s_nop 0
	v_fmac_f32_e32 v133, v126, v0
	v_and_b32_e32 v0, 0xffff0000, v164
	v_mul_f32_e32 v0, 0xbfb8aa3b, v0
	v_exp_f32_e32 v0, v0
	v_cvt_pk_bf16_f32 v126, v121, v130
	v_lshlrev_b32_e32 v121, 16, v150
	v_add_f32_e32 v0, 1.0, v0
	v_rcp_f32_e32 v0, v0
	s_nop 0
	v_fmac_f32_e32 v158, v127, v0
	v_lshlrev_b32_e32 v0, 16, v165
	v_mul_f32_e32 v0, 0xbfb8aa3b, v0
	v_exp_f32_e32 v0, v0
	v_cvt_pk_bf16_f32 v127, v131, v132
	s_nop 0
	v_add_f32_e32 v0, 1.0, v0
	v_rcp_f32_e32 v0, v0
	s_nop 0
	v_fmac_f32_e32 v159, v128, v0
	v_and_b32_e32 v0, 0xffff0000, v165
	v_mul_f32_e32 v0, 0xbfb8aa3b, v0
	v_exp_f32_e32 v0, v0
	v_cvt_pk_bf16_f32 v128, v133, v158
	s_nop 0
	v_add_f32_e32 v0, 1.0, v0
	v_rcp_f32_e32 v0, v0
	s_nop 0
	v_fmac_f32_e32 v160, v129, v0
	v_lshlrev_b32_e32 v0, 16, v154
	v_mul_f32_e32 v0, 0xbfb8aa3b, v0
	v_exp_f32_e32 v0, v0
	v_cvt_pk_bf16_f32 v129, v159, v160
	v_lshlrev_b64 v[158:159], 1, v[2:3]
	v_lshl_add_u64 v[130:131], v[192:193], 0, v[158:159]
	v_add_f32_e32 v0, 1.0, v0
	v_rcp_f32_e32 v0, v0
	global_store_dwordx4 v[130:131], v[126:129], off sc0 sc1
	v_fmac_f32_e32 v121, v122, v0
	v_and_b32_e32 v0, 0xffff0000, v154
	v_mul_f32_e32 v0, 0xbfb8aa3b, v0
	v_exp_f32_e32 v0, v0
	v_and_b32_e32 v122, 0xffff0000, v150
	v_and_b32_e32 v126, 0xffff0000, v152
	v_lshlrev_b32_e32 v127, 16, v153
	v_add_f32_e32 v0, 1.0, v0
	v_rcp_f32_e32 v0, v0
	v_and_b32_e32 v128, 0xffff0000, v153
	v_fmac_f32_e32 v122, v123, v0
	v_lshlrev_b32_e32 v0, 16, v155
	v_mul_f32_e32 v0, 0xbfb8aa3b, v0
	v_exp_f32_e32 v0, v0
	v_lshlrev_b32_e32 v123, 16, v151
	v_add_f32_e32 v0, 1.0, v0
	v_rcp_f32_e32 v0, v0
	s_nop 0
	v_fmac_f32_e32 v123, v124, v0
	v_and_b32_e32 v0, 0xffff0000, v155
	v_mul_f32_e32 v0, 0xbfb8aa3b, v0
	v_exp_f32_e32 v0, v0
	v_and_b32_e32 v124, 0xffff0000, v151
	v_add_f32_e32 v0, 1.0, v0
	v_rcp_f32_e32 v0, v0
	s_nop 0
	v_fmac_f32_e32 v124, v125, v0
	v_lshlrev_b32_e32 v0, 16, v156
	v_mul_f32_e32 v0, 0xbfb8aa3b, v0
	v_exp_f32_e32 v0, v0
	v_lshlrev_b32_e32 v125, 16, v152
	v_add_f32_e32 v0, 1.0, v0
	v_rcp_f32_e32 v0, v0
	s_nop 0
	v_fmac_f32_e32 v125, v116, v0
	v_and_b32_e32 v0, 0xffff0000, v156
	v_mul_f32_e32 v0, 0xbfb8aa3b, v0
	v_exp_f32_e32 v0, v0
	v_cvt_pk_bf16_f32 v116, v121, v122
	v_mov_b32_e32 v121, 0
	v_mov_b32_e32 v122, 0
	v_add_f32_e32 v0, 1.0, v0
	v_rcp_f32_e32 v0, v0
	s_nop 0
	v_fmac_f32_e32 v126, v117, v0
; __device__ __forceinline__ unsigned pk2(float lo, float hi) { unsigned r; asm("v_cvt_pk_bf16_f32 %0, %1, %2" : "=v"(r) : "v"(lo), "v"(hi)); return r; }
; __device__ __forceinline__ float bflo(unsigned w) { return __uint_as_float(w << 16); }
; __device__ __forceinline__ float bfhi(unsigned w) { return __uint_as_float(w & 0xffff0000u); }
; __device__ __forceinline__ float sigmoidf_(float x) { return __builtin_amdgcn_rcpf(1.f + __expf(-x)); }
;     __device__ __forceinline__ void operator()(const f32x4 (&acc)[2][2][4][2], const Unit& u, int wr, int wc, int fr, int fq) const {
;     ...
;             for (int mm = 0; mm < 2; ++mm) { const int row = row0 + ai * HALF + (2 * mp + mm) * 16;
; #pragma unroll
;                 for (int bj = 0; bj < 2; ++bj) { const int col = col0 + bj * HALF;
;                     gw[mm][bj] = *(const u32x4*)(proj + (size_t)row * PN + gbase + col);
;                     pw[mm][bj] = u.part == 1 ? *(const u32x4*)(mix + (size_t)row * DM + col) : (u32x4){0u, 0u, 0u, 0u}; } }
; #pragma unroll
;             for (int mm = 0; mm < 2; ++mm) { const int m = 2 * mp + mm; const int row = row0 + ai * HALF + m * 16;
; #pragma unroll
;                 for (int bj = 0; bj < 2; ++bj) { const int col = col0 + bj * HALF;
;                     const u32x4 g = gw[mm][bj], p = pw[mm][bj];
;                     const f32x4 v0 = acc[ai][bj][m][0], v1 = acc[ai][bj][m][1];
;                     float r[8];
;                     r[0] = sigmoidf_(bflo(g.x)) * v0[0] + bflo(p.x); r[1] = sigmoidf_(bfhi(g.x)) * v0[1] + bfhi(p.x); r[2] = sigmoidf_(bflo(g.y)) * v0[2] + bflo(p.y); r[3] = sigmoidf_(bfhi(g.y)) * v0[3] + bfhi(p.y);
;                     r[4] = sigmoidf_(bflo(g.z)) * v1[0] + bflo(p.z); r[5] = sigmoidf_(bfhi(g.z)) * v1[1] + bfhi(p.z); r[6] = sigmoidf_(bflo(g.w)) * v1[2] + bflo(p.w); r[7] = sigmoidf_(bfhi(g.w)) * v1[3] + bfhi(p.w);
;                     u32x4 w; w.x = pk2(r[0], r[1]); w.y = pk2(r[2], r[3]); w.z = pk2(r[4], r[5]); w.w = pk2(r[6], r[7]);
;                     *(u32x4*)(mix + (size_t)row * DM + col) = w; } }
	v_lshlrev_b32_e32 v0, 16, v157
	v_mul_f32_e32 v0, 0xbfb8aa3b, v0
	v_exp_f32_e32 v0, v0
	v_cvt_pk_bf16_f32 v117, v123, v124
	v_mov_b32_e32 v123, 0
	v_add_f32_e32 v0, 1.0, v0
	v_rcp_f32_e32 v0, v0
	s_nop 0
	v_fmac_f32_e32 v127, v118, v0
	v_and_b32_e32 v0, 0xffff0000, v157
	v_mul_f32_e32 v0, 0xbfb8aa3b, v0
	v_exp_f32_e32 v0, v0
	v_cvt_pk_bf16_f32 v118, v125, v126
	s_nop 0
	v_add_f32_e32 v0, 1.0, v0
	v_rcp_f32_e32 v0, v0
	s_nop 0
	v_fmac_f32_e32 v128, v119, v0
	v_lshlrev_b32_e32 v0, 16, v146
	v_mul_f32_e32 v0, 0xbfb8aa3b, v0
	v_exp_f32_e32 v0, v0
	v_cvt_pk_bf16_f32 v119, v127, v128
	global_store_dwordx4 v[130:131], v[116:119], off offset:256 sc0 sc1
	v_add_f32_e32 v0, 1.0, v0
	v_rcp_f32_e32 v0, v0
	v_lshlrev_b32_e32 v116, 16, v142
	v_and_b32_e32 v117, 0xffff0000, v144
	v_lshlrev_b32_e32 v118, 16, v145
	v_fmac_f32_e32 v116, v112, v0
	v_and_b32_e32 v0, 0xffff0000, v146
	v_mul_f32_e32 v0, 0xbfb8aa3b, v0
	v_exp_f32_e32 v0, v0
	v_and_b32_e32 v112, 0xffff0000, v142
	v_and_b32_e32 v119, 0xffff0000, v145
	v_add_f32_e32 v0, 1.0, v0
	v_rcp_f32_e32 v0, v0
	s_nop 0
	v_fmac_f32_e32 v112, v113, v0
	v_lshlrev_b32_e32 v0, 16, v147
	v_mul_f32_e32 v0, 0xbfb8aa3b, v0
	v_exp_f32_e32 v0, v0
	v_lshlrev_b32_e32 v113, 16, v143
	v_add_f32_e32 v0, 1.0, v0
	v_rcp_f32_e32 v0, v0
	s_nop 0
	v_fmac_f32_e32 v113, v114, v0
	v_and_b32_e32 v0, 0xffff0000, v147
	v_mul_f32_e32 v0, 0xbfb8aa3b, v0
	v_exp_f32_e32 v0, v0
	v_and_b32_e32 v114, 0xffff0000, v143
	v_add_f32_e32 v0, 1.0, v0
	v_rcp_f32_e32 v0, v0
	s_nop 0
	v_fmac_f32_e32 v114, v115, v0
	v_lshlrev_b32_e32 v0, 16, v148
	v_mul_f32_e32 v0, 0xbfb8aa3b, v0
	v_exp_f32_e32 v0, v0
	v_lshlrev_b32_e32 v115, 16, v144
	v_add_f32_e32 v0, 1.0, v0
	v_rcp_f32_e32 v0, v0
	s_nop 0
	v_fmac_f32_e32 v115, v108, v0
	v_and_b32_e32 v0, 0xffff0000, v148
	v_mul_f32_e32 v0, 0xbfb8aa3b, v0
	v_exp_f32_e32 v0, v0
	v_cvt_pk_bf16_f32 v108, v116, v112
	s_nop 0
	v_add_f32_e32 v0, 1.0, v0
	v_rcp_f32_e32 v0, v0
	s_nop 0
	v_fmac_f32_e32 v117, v109, v0
	v_lshlrev_b32_e32 v0, 16, v149
	v_mul_f32_e32 v0, 0xbfb8aa3b, v0
	v_exp_f32_e32 v0, v0
	v_cvt_pk_bf16_f32 v109, v113, v114
	v_lshl_add_u64 v[112:113], v[190:191], 0, v[158:159]
	v_add_f32_e32 v0, 1.0, v0
	v_rcp_f32_e32 v0, v0
	s_nop 0
	v_fmac_f32_e32 v118, v110, v0
	v_and_b32_e32 v0, 0xffff0000, v149
	v_mul_f32_e32 v0, 0xbfb8aa3b, v0
	v_exp_f32_e32 v0, v0
	v_cvt_pk_bf16_f32 v110, v115, v117
	s_nop 0
	v_add_f32_e32 v0, 1.0, v0
	v_rcp_f32_e32 v0, v0
	s_nop 0
	v_fmac_f32_e32 v119, v111, v0
	v_lshlrev_b32_e32 v0, 16, v138
	v_mul_f32_e32 v0, 0xbfb8aa3b, v0
	v_exp_f32_e32 v0, v0
	v_cvt_pk_bf16_f32 v111, v118, v119
	global_store_dwordx4 v[112:113], v[108:111], off sc0 sc1
	v_add_f32_e32 v0, 1.0, v0
	v_rcp_f32_e32 v0, v0
	v_lshlrev_b32_e32 v108, 16, v134
	v_and_b32_e32 v109, 0xffff0000, v136
	v_lshlrev_b32_e32 v110, 16, v137
	v_fmac_f32_e32 v108, v104, v0
	v_and_b32_e32 v0, 0xffff0000, v138
	v_mul_f32_e32 v0, 0xbfb8aa3b, v0
	v_exp_f32_e32 v0, v0
	v_and_b32_e32 v104, 0xffff0000, v134
	v_and_b32_e32 v111, 0xffff0000, v137
	v_add_f32_e32 v0, 1.0, v0
	v_rcp_f32_e32 v0, v0
	s_nop 0
	v_fmac_f32_e32 v104, v105, v0
	v_lshlrev_b32_e32 v0, 16, v139
	v_mul_f32_e32 v0, 0xbfb8aa3b, v0
	v_exp_f32_e32 v0, v0
	v_lshlrev_b32_e32 v105, 16, v135
	v_add_f32_e32 v0, 1.0, v0
	v_rcp_f32_e32 v0, v0
	s_nop 0
	v_fmac_f32_e32 v105, v106, v0
	v_and_b32_e32 v0, 0xffff0000, v139
	v_mul_f32_e32 v0, 0xbfb8aa3b, v0
	v_exp_f32_e32 v0, v0
	v_and_b32_e32 v106, 0xffff0000, v135
	v_add_f32_e32 v0, 1.0, v0
	v_rcp_f32_e32 v0, v0
	s_nop 0
	v_fmac_f32_e32 v106, v107, v0
	v_lshlrev_b32_e32 v0, 16, v140
	v_mul_f32_e32 v0, 0xbfb8aa3b, v0
	v_exp_f32_e32 v0, v0
	v_lshlrev_b32_e32 v107, 16, v136
	v_add_f32_e32 v0, 1.0, v0
	v_rcp_f32_e32 v0, v0
	s_nop 0
	v_fmac_f32_e32 v107, v100, v0
	v_and_b32_e32 v0, 0xffff0000, v140
	v_mul_f32_e32 v0, 0xbfb8aa3b, v0
	v_exp_f32_e32 v0, v0
	v_cvt_pk_bf16_f32 v100, v108, v104
	s_nop 0
	v_add_f32_e32 v0, 1.0, v0
	v_rcp_f32_e32 v0, v0
	s_nop 0
	v_fmac_f32_e32 v109, v101, v0
	v_lshlrev_b32_e32 v0, 16, v141
	v_mul_f32_e32 v0, 0xbfb8aa3b, v0
	v_exp_f32_e32 v0, v0
	v_cvt_pk_bf16_f32 v101, v105, v106
	s_nop 0
	v_add_f32_e32 v0, 1.0, v0
	v_rcp_f32_e32 v0, v0
	s_nop 0
	v_fmac_f32_e32 v110, v102, v0
	v_and_b32_e32 v0, 0xffff0000, v141
	v_mul_f32_e32 v0, 0xbfb8aa3b, v0
	v_exp_f32_e32 v0, v0
	v_cvt_pk_bf16_f32 v102, v107, v109
	s_nop 0
	v_add_f32_e32 v0, 1.0, v0
	v_rcp_f32_e32 v0, v0
	s_nop 0
	v_fmac_f32_e32 v111, v103, v0
	v_cvt_pk_bf16_f32 v103, v110, v111
	global_store_dwordx4 v[112:113], v[100:103], off offset:256 sc0 sc1
	s_nop 1
	v_or_b32_e32 v100, 32, v188
	v_ashrrev_i32_e32 v101, 31, v100
	v_mov_b64_e32 v[102:103], s[4:5]
	v_mad_i64_i32 v[102:103], s[8:9], v100, s33, v[102:103]
	v_lshlrev_b64 v[100:101], 11, v[100:101]
	v_lshl_add_u64 v[136:137], s[12:13], 0, v[100:101]
	v_lshl_add_u64 v[100:101], v[102:103], 0, v[158:159]
	global_load_dwordx4 v[132:135], v[100:101], off
	v_lshl_add_u64 v[102:103], v[2:3], 1, v[136:137]
	s_cbranch_vccnz .LBB0_694
	global_load_dwordx4 v[120:123], v[102:103], off sc0 sc1
.LBB0_694:
	global_load_dwordx4 v[128:131], v[100:101], off offset:256
	v_mov_b32_e32 v110, 0
	s_and_b64 vcc, exec, s[42:43]
	v_mov_b32_e32 v124, 0
	v_mov_b32_e32 v125, 0
	v_mov_b32_e32 v126, 0
	v_mov_b32_e32 v127, 0
	s_cbranch_vccnz .LBB0_696
	global_load_dwordx4 v[124:127], v[102:103], off offset:256 sc0 sc1
.LBB0_696:
	v_or_b32_e32 v102, 48, v188
	v_mov_b64_e32 v[100:101], s[4:5]
	v_mad_i64_i32 v[100:101], s[8:9], v102, s33, v[100:101]
	v_lshl_add_u64 v[100:101], v[2:3], 1, v[100:101]
	global_load_dwordx4 v[114:117], v[100:101], off
	v_ashrrev_i32_e32 v103, 31, v102
	v_lshlrev_b64 v[102:103], 11, v[102:103]
	v_lshl_add_u64 v[118:119], s[12:13], 0, v[102:103]
	s_and_b64 vcc, exec, s[42:43]
	v_lshl_add_u64 v[138:139], v[2:3], 1, v[118:119]
	v_mov_b32_e32 v111, 0
	v_mov_b32_e32 v112, 0
	v_mov_b32_e32 v113, 0
	s_cbranch_vccnz .LBB0_698
	global_load_dwordx4 v[110:113], v[138:139], off sc0 sc1
; __device__ __forceinline__ unsigned pk2(float lo, float hi) { unsigned r; asm("v_cvt_pk_bf16_f32 %0, %1, %2" : "=v"(r) : "v"(lo), "v"(hi)); return r; }
; __device__ __forceinline__ float bflo(unsigned w) { return __uint_as_float(w << 16); }
; __device__ __forceinline__ float bfhi(unsigned w) { return __uint_as_float(w & 0xffff0000u); }
; __device__ __forceinline__ float sigmoidf_(float x) { return __builtin_amdgcn_rcpf(1.f + __expf(-x)); }
;     __device__ __forceinline__ void operator()(const f32x4 (&acc)[2][2][4][2], const Unit& u, int wr, int wc, int fr, int fq) const {
;     ...
;             for (int mm = 0; mm < 2; ++mm) { const int row = row0 + ai * HALF + (2 * mp + mm) * 16;
; #pragma unroll
;                 for (int bj = 0; bj < 2; ++bj) { const int col = col0 + bj * HALF;
;                     gw[mm][bj] = *(const u32x4*)(proj + (size_t)row * PN + gbase + col);
;                     pw[mm][bj] = u.part == 1 ? *(const u32x4*)(mix + (size_t)row * DM + col) : (u32x4){0u, 0u, 0u, 0u}; } }
; #pragma unroll
;             for (int mm = 0; mm < 2; ++mm) { const int m = 2 * mp + mm; const int row = row0 + ai * HALF + m * 16;
; #pragma unroll
;                 for (int bj = 0; bj < 2; ++bj) { const int col = col0 + bj * HALF;
;                     const u32x4 g = gw[mm][bj], p = pw[mm][bj];
;                     const f32x4 v0 = acc[ai][bj][m][0], v1 = acc[ai][bj][m][1];
;                     float r[8];
;                     r[0] = sigmoidf_(bflo(g.x)) * v0[0] + bflo(p.x); r[1] = sigmoidf_(bfhi(g.x)) * v0[1] + bfhi(p.x); r[2] = sigmoidf_(bflo(g.y)) * v0[2] + bflo(p.y); r[3] = sigmoidf_(bfhi(g.y)) * v0[3] + bfhi(p.y);
;                     r[4] = sigmoidf_(bflo(g.z)) * v1[0] + bflo(p.z); r[5] = sigmoidf_(bfhi(g.z)) * v1[1] + bfhi(p.z); r[6] = sigmoidf_(bflo(g.w)) * v1[2] + bflo(p.w); r[7] = sigmoidf_(bfhi(g.w)) * v1[3] + bfhi(p.w);
;                     u32x4 w; w.x = pk2(r[0], r[1]); w.y = pk2(r[2], r[3]); w.z = pk2(r[4], r[5]); w.w = pk2(r[6], r[7]);
;                     *(u32x4*)(mix + (size_t)row * DM + col) = w; } }
.LBB0_698:
	global_load_dwordx4 v[106:109], v[100:101], off offset:256
	v_mov_b32_e32 v100, 0
	s_and_b64 vcc, exec, s[42:43]
	v_mov_b32_e32 v102, 0
	v_mov_b32_e32 v103, 0
	v_mov_b32_e32 v104, 0
	v_mov_b32_e32 v105, 0
	s_cbranch_vccnz .LBB0_700
	global_load_dwordx4 v[102:105], v[138:139], off offset:256 sc0 sc1
.LBB0_700:
	s_waitcnt vmcnt(3)
	v_lshlrev_b32_e32 v0, 16, v132
	v_mul_f32_e32 v0, 0xbfb8aa3b, v0
	v_exp_f32_e32 v0, v0
	v_lshlrev_b32_e32 v101, 16, v120
	s_and_b64 vcc, exec, s[42:43]
	v_add_f32_e32 v0, 1.0, v0
	v_rcp_f32_e32 v0, v0
	s_nop 0
	v_fmac_f32_e32 v101, v96, v0
	v_and_b32_e32 v0, 0xffff0000, v132
	v_mul_f32_e32 v0, 0xbfb8aa3b, v0
	v_exp_f32_e32 v0, v0
	v_and_b32_e32 v96, 0xffff0000, v120
	v_and_b32_e32 v120, 0xffff0000, v122
	v_add_f32_e32 v0, 1.0, v0
	v_rcp_f32_e32 v0, v0
	s_nop 0
	v_fmac_f32_e32 v96, v97, v0
	v_lshlrev_b32_e32 v0, 16, v133
	v_mul_f32_e32 v0, 0xbfb8aa3b, v0
	v_exp_f32_e32 v0, v0
	v_lshlrev_b32_e32 v97, 16, v121
	v_add_f32_e32 v0, 1.0, v0
	v_rcp_f32_e32 v0, v0
	s_nop 0
	v_fmac_f32_e32 v97, v98, v0
	v_and_b32_e32 v0, 0xffff0000, v133
	v_mul_f32_e32 v0, 0xbfb8aa3b, v0
	v_exp_f32_e32 v0, v0
	v_and_b32_e32 v98, 0xffff0000, v121
	v_lshlrev_b32_e32 v121, 16, v123
	v_add_f32_e32 v0, 1.0, v0
	v_rcp_f32_e32 v0, v0
	s_nop 0
	v_fmac_f32_e32 v98, v99, v0
	v_lshlrev_b32_e32 v0, 16, v134
	v_mul_f32_e32 v0, 0xbfb8aa3b, v0
	v_exp_f32_e32 v0, v0
	v_lshlrev_b32_e32 v99, 16, v122
	v_and_b32_e32 v122, 0xffff0000, v123
	v_add_f32_e32 v0, 1.0, v0
	v_rcp_f32_e32 v0, v0
	s_nop 0
	v_fmac_f32_e32 v99, v92, v0
	v_and_b32_e32 v0, 0xffff0000, v134
	v_mul_f32_e32 v0, 0xbfb8aa3b, v0
	v_exp_f32_e32 v0, v0
	v_cvt_pk_bf16_f32 v92, v101, v96
	v_mov_b32_e32 v101, 0
	v_add_f32_e32 v0, 1.0, v0
	v_rcp_f32_e32 v0, v0
	s_nop 0
	v_fmac_f32_e32 v120, v93, v0
	v_lshlrev_b32_e32 v0, 16, v135
	v_mul_f32_e32 v0, 0xbfb8aa3b, v0
	v_exp_f32_e32 v0, v0
	v_cvt_pk_bf16_f32 v93, v97, v98
	v_lshl_add_u64 v[96:97], v[136:137], 0, v[158:159]
	v_add_f32_e32 v0, 1.0, v0
	v_rcp_f32_e32 v0, v0
	s_nop 0
	v_fmac_f32_e32 v121, v94, v0
	v_and_b32_e32 v0, 0xffff0000, v135
	v_mul_f32_e32 v0, 0xbfb8aa3b, v0
	v_exp_f32_e32 v0, v0
	v_cvt_pk_bf16_f32 v94, v99, v120
	s_nop 0
	v_add_f32_e32 v0, 1.0, v0
	v_rcp_f32_e32 v0, v0
	s_nop 0
	v_fmac_f32_e32 v122, v95, v0
	s_waitcnt vmcnt(2)
	v_lshlrev_b32_e32 v0, 16, v128
	v_mul_f32_e32 v0, 0xbfb8aa3b, v0
	v_exp_f32_e32 v0, v0
	v_cvt_pk_bf16_f32 v95, v121, v122
	global_store_dwordx4 v[96:97], v[92:95], off sc0 sc1
	v_add_f32_e32 v0, 1.0, v0
	v_rcp_f32_e32 v0, v0
	v_lshlrev_b32_e32 v92, 16, v124
	v_and_b32_e32 v93, 0xffff0000, v126
	v_lshlrev_b32_e32 v94, 16, v127
	v_fmac_f32_e32 v92, v88, v0
	v_and_b32_e32 v0, 0xffff0000, v128
	v_mul_f32_e32 v0, 0xbfb8aa3b, v0
	v_exp_f32_e32 v0, v0
	v_and_b32_e32 v88, 0xffff0000, v124
	v_and_b32_e32 v95, 0xffff0000, v127
	v_add_f32_e32 v0, 1.0, v0
	v_rcp_f32_e32 v0, v0
	s_nop 0
	v_fmac_f32_e32 v88, v89, v0
	v_lshlrev_b32_e32 v0, 16, v129
	v_mul_f32_e32 v0, 0xbfb8aa3b, v0
	v_exp_f32_e32 v0, v0
	v_lshlrev_b32_e32 v89, 16, v125
	v_add_f32_e32 v0, 1.0, v0
	v_rcp_f32_e32 v0, v0
	s_nop 0
	v_fmac_f32_e32 v89, v90, v0
	v_and_b32_e32 v0, 0xffff0000, v129
	v_mul_f32_e32 v0, 0xbfb8aa3b, v0
	v_exp_f32_e32 v0, v0
	v_and_b32_e32 v90, 0xffff0000, v125
	v_add_f32_e32 v0, 1.0, v0
	v_rcp_f32_e32 v0, v0
	s_nop 0
	v_fmac_f32_e32 v90, v91, v0
	v_lshlrev_b32_e32 v0, 16, v130
	v_mul_f32_e32 v0, 0xbfb8aa3b, v0
	v_exp_f32_e32 v0, v0
	v_lshlrev_b32_e32 v91, 16, v126
	v_add_f32_e32 v0, 1.0, v0
	v_rcp_f32_e32 v0, v0
	s_nop 0
	v_fmac_f32_e32 v91, v84, v0
	v_and_b32_e32 v0, 0xffff0000, v130
	v_mul_f32_e32 v0, 0xbfb8aa3b, v0
	v_exp_f32_e32 v0, v0
	v_cvt_pk_bf16_f32 v84, v92, v88
	s_nop 0
	v_add_f32_e32 v0, 1.0, v0
	v_rcp_f32_e32 v0, v0
	s_nop 0
	v_fmac_f32_e32 v93, v85, v0
	v_lshlrev_b32_e32 v0, 16, v131
	v_mul_f32_e32 v0, 0xbfb8aa3b, v0
	v_exp_f32_e32 v0, v0
	v_cvt_pk_bf16_f32 v85, v89, v90
	s_nop 0
	v_add_f32_e32 v0, 1.0, v0
	v_rcp_f32_e32 v0, v0
	s_nop 0
	v_fmac_f32_e32 v94, v86, v0
	v_and_b32_e32 v0, 0xffff0000, v131
	v_mul_f32_e32 v0, 0xbfb8aa3b, v0
	v_exp_f32_e32 v0, v0
	v_cvt_pk_bf16_f32 v86, v91, v93
	s_nop 0
	v_add_f32_e32 v0, 1.0, v0
	v_rcp_f32_e32 v0, v0
	s_nop 0
	v_fmac_f32_e32 v95, v87, v0
	s_waitcnt vmcnt(2)
	v_lshlrev_b32_e32 v0, 16, v114
	v_mul_f32_e32 v0, 0xbfb8aa3b, v0
	v_exp_f32_e32 v0, v0
	v_cvt_pk_bf16_f32 v87, v94, v95
	global_store_dwordx4 v[96:97], v[84:87], off offset:256 sc0 sc1
	v_add_f32_e32 v0, 1.0, v0
	v_rcp_f32_e32 v0, v0
	v_lshlrev_b32_e32 v84, 16, v110
	v_and_b32_e32 v85, 0xffff0000, v112
	v_lshlrev_b32_e32 v86, 16, v113
	v_fmac_f32_e32 v84, v80, v0
	v_and_b32_e32 v0, 0xffff0000, v114
	v_mul_f32_e32 v0, 0xbfb8aa3b, v0
	v_exp_f32_e32 v0, v0
	v_and_b32_e32 v80, 0xffff0000, v110
	v_and_b32_e32 v87, 0xffff0000, v113
	v_add_f32_e32 v0, 1.0, v0
	v_rcp_f32_e32 v0, v0
	s_nop 0
	v_fmac_f32_e32 v80, v81, v0
	v_lshlrev_b32_e32 v0, 16, v115
	v_mul_f32_e32 v0, 0xbfb8aa3b, v0
	v_exp_f32_e32 v0, v0
	v_lshlrev_b32_e32 v81, 16, v111
	v_add_f32_e32 v0, 1.0, v0
	v_rcp_f32_e32 v0, v0
	s_nop 0
	v_fmac_f32_e32 v81, v82, v0
	v_and_b32_e32 v0, 0xffff0000, v115
	v_mul_f32_e32 v0, 0xbfb8aa3b, v0
	v_exp_f32_e32 v0, v0
	v_and_b32_e32 v82, 0xffff0000, v111
	v_add_f32_e32 v0, 1.0, v0
	v_rcp_f32_e32 v0, v0
	s_nop 0
	v_fmac_f32_e32 v82, v83, v0
	v_lshlrev_b32_e32 v0, 16, v116
	v_mul_f32_e32 v0, 0xbfb8aa3b, v0
	v_exp_f32_e32 v0, v0
	v_lshlrev_b32_e32 v83, 16, v112
	v_add_f32_e32 v0, 1.0, v0
	v_rcp_f32_e32 v0, v0
	s_nop 0
	v_fmac_f32_e32 v83, v76, v0
	v_and_b32_e32 v0, 0xffff0000, v116
	v_mul_f32_e32 v0, 0xbfb8aa3b, v0
	v_exp_f32_e32 v0, v0
	v_cvt_pk_bf16_f32 v76, v84, v80
	s_nop 0
	v_add_f32_e32 v0, 1.0, v0
	v_rcp_f32_e32 v0, v0
	s_nop 0
	v_fmac_f32_e32 v85, v77, v0
	v_lshlrev_b32_e32 v0, 16, v117
	v_mul_f32_e32 v0, 0xbfb8aa3b, v0
	v_exp_f32_e32 v0, v0
	v_cvt_pk_bf16_f32 v77, v81, v82
	v_lshl_add_u64 v[80:81], v[118:119], 0, v[158:159]
	v_add_f32_e32 v0, 1.0, v0
	v_rcp_f32_e32 v0, v0
	s_nop 0
	v_fmac_f32_e32 v86, v78, v0
	v_and_b32_e32 v0, 0xffff0000, v117
	v_mul_f32_e32 v0, 0xbfb8aa3b, v0
	v_exp_f32_e32 v0, v0
	v_cvt_pk_bf16_f32 v78, v83, v85
	s_nop 0
	v_add_f32_e32 v0, 1.0, v0
	v_rcp_f32_e32 v0, v0
	s_nop 0
	v_fmac_f32_e32 v87, v79, v0
	s_waitcnt vmcnt(2)
; __device__ __forceinline__ unsigned pk2(float lo, float hi) { unsigned r; asm("v_cvt_pk_bf16_f32 %0, %1, %2" : "=v"(r) : "v"(lo), "v"(hi)); return r; }
; __device__ __forceinline__ float bflo(unsigned w) { return __uint_as_float(w << 16); }
; __device__ __forceinline__ float bfhi(unsigned w) { return __uint_as_float(w & 0xffff0000u); }
; __device__ __forceinline__ float sigmoidf_(float x) { return __builtin_amdgcn_rcpf(1.f + __expf(-x)); }
;     __device__ __forceinline__ void operator()(const f32x4 (&acc)[2][2][4][2], const Unit& u, int wr, int wc, int fr, int fq) const {
;     ...
;             for (int mm = 0; mm < 2; ++mm) { const int row = row0 + ai * HALF + (2 * mp + mm) * 16;
; #pragma unroll
;                 for (int bj = 0; bj < 2; ++bj) { const int col = col0 + bj * HALF;
;                     gw[mm][bj] = *(const u32x4*)(proj + (size_t)row * PN + gbase + col);
;                     pw[mm][bj] = u.part == 1 ? *(const u32x4*)(mix + (size_t)row * DM + col) : (u32x4){0u, 0u, 0u, 0u}; } }
; #pragma unroll
;             for (int mm = 0; mm < 2; ++mm) { const int m = 2 * mp + mm; const int row = row0 + ai * HALF + m * 16;
; #pragma unroll
;                 for (int bj = 0; bj < 2; ++bj) { const int col = col0 + bj * HALF;
;                     const u32x4 g = gw[mm][bj], p = pw[mm][bj];
;                     const f32x4 v0 = acc[ai][bj][m][0], v1 = acc[ai][bj][m][1];
;                     float r[8];
;                     r[0] = sigmoidf_(bflo(g.x)) * v0[0] + bflo(p.x); r[1] = sigmoidf_(bfhi(g.x)) * v0[1] + bfhi(p.x); r[2] = sigmoidf_(bflo(g.y)) * v0[2] + bflo(p.y); r[3] = sigmoidf_(bfhi(g.y)) * v0[3] + bfhi(p.y);
;                     r[4] = sigmoidf_(bflo(g.z)) * v1[0] + bflo(p.z); r[5] = sigmoidf_(bfhi(g.z)) * v1[1] + bfhi(p.z); r[6] = sigmoidf_(bflo(g.w)) * v1[2] + bflo(p.w); r[7] = sigmoidf_(bfhi(g.w)) * v1[3] + bfhi(p.w);
;                     u32x4 w; w.x = pk2(r[0], r[1]); w.y = pk2(r[2], r[3]); w.z = pk2(r[4], r[5]); w.w = pk2(r[6], r[7]);
;                     *(u32x4*)(mix + (size_t)row * DM + col) = w; } }
	v_lshlrev_b32_e32 v0, 16, v106
	v_mul_f32_e32 v0, 0xbfb8aa3b, v0
	v_exp_f32_e32 v0, v0
	v_cvt_pk_bf16_f32 v79, v86, v87
	global_store_dwordx4 v[80:81], v[76:79], off sc0 sc1
	v_add_f32_e32 v0, 1.0, v0
	v_rcp_f32_e32 v0, v0
	v_lshlrev_b32_e32 v76, 16, v102
	v_and_b32_e32 v77, 0xffff0000, v104
	v_lshlrev_b32_e32 v78, 16, v105
	v_fmac_f32_e32 v76, v72, v0
	v_and_b32_e32 v0, 0xffff0000, v106
	v_mul_f32_e32 v0, 0xbfb8aa3b, v0
	v_exp_f32_e32 v0, v0
	v_and_b32_e32 v72, 0xffff0000, v102
	v_and_b32_e32 v79, 0xffff0000, v105
	v_mov_b32_e32 v102, 0
	v_add_f32_e32 v0, 1.0, v0
	v_rcp_f32_e32 v0, v0
	s_nop 0
	v_fmac_f32_e32 v72, v73, v0
	v_lshlrev_b32_e32 v0, 16, v107
	v_mul_f32_e32 v0, 0xbfb8aa3b, v0
	v_exp_f32_e32 v0, v0
	v_lshlrev_b32_e32 v73, 16, v103
	v_add_f32_e32 v0, 1.0, v0
	v_rcp_f32_e32 v0, v0
	s_nop 0
	v_fmac_f32_e32 v73, v74, v0
	v_and_b32_e32 v0, 0xffff0000, v107
	v_mul_f32_e32 v0, 0xbfb8aa3b, v0
	v_exp_f32_e32 v0, v0
	v_and_b32_e32 v74, 0xffff0000, v103
	v_mov_b32_e32 v103, 0
	v_add_f32_e32 v0, 1.0, v0
	v_rcp_f32_e32 v0, v0
	s_nop 0
	v_fmac_f32_e32 v74, v75, v0
	v_lshlrev_b32_e32 v0, 16, v108
	v_mul_f32_e32 v0, 0xbfb8aa3b, v0
	v_exp_f32_e32 v0, v0
	v_lshlrev_b32_e32 v75, 16, v104
	v_add_f32_e32 v0, 1.0, v0
	v_rcp_f32_e32 v0, v0
	s_nop 0
	v_fmac_f32_e32 v75, v68, v0
	v_and_b32_e32 v0, 0xffff0000, v108
	v_mul_f32_e32 v0, 0xbfb8aa3b, v0
	v_exp_f32_e32 v0, v0
	v_cvt_pk_bf16_f32 v68, v76, v72
	s_nop 0
	v_add_f32_e32 v0, 1.0, v0
	v_rcp_f32_e32 v0, v0
	s_nop 0
	v_fmac_f32_e32 v77, v69, v0
	v_lshlrev_b32_e32 v0, 16, v109
	v_mul_f32_e32 v0, 0xbfb8aa3b, v0
	v_exp_f32_e32 v0, v0
	v_cvt_pk_bf16_f32 v69, v73, v74
	s_nop 0
	v_add_f32_e32 v0, 1.0, v0
	v_rcp_f32_e32 v0, v0
	s_nop 0
	v_fmac_f32_e32 v78, v70, v0
	v_and_b32_e32 v0, 0xffff0000, v109
	v_mul_f32_e32 v0, 0xbfb8aa3b, v0
	v_exp_f32_e32 v0, v0
	v_cvt_pk_bf16_f32 v70, v75, v77
	s_nop 0
	v_add_f32_e32 v0, 1.0, v0
	v_rcp_f32_e32 v0, v0
	s_nop 0
	v_fmac_f32_e32 v79, v71, v0
	v_cvt_pk_bf16_f32 v71, v78, v79
	global_store_dwordx4 v[80:81], v[68:71], off offset:256 sc0 sc1
	s_nop 1
	v_add_u32_e32 v68, 0x80, v188
	v_ashrrev_i32_e32 v69, 31, v68
	v_mov_b64_e32 v[70:71], s[4:5]
	v_mad_i64_i32 v[70:71], s[8:9], v68, s33, v[70:71]
	v_lshlrev_b64 v[68:69], 11, v[68:69]
	v_lshl_add_u64 v[104:105], s[12:13], 0, v[68:69]
	v_lshl_add_u64 v[68:69], v[70:71], 0, v[158:159]
	global_load_dwordx4 v[94:97], v[68:69], off
	v_lshl_add_u64 v[70:71], v[2:3], 1, v[104:105]
	s_cbranch_vccnz .LBB0_702
	global_load_dwordx4 v[100:103], v[70:71], off sc0 sc1
.LBB0_702:
	global_load_dwordx4 v[90:93], v[68:69], off offset:256
	v_mov_b32_e32 v78, 0
	s_and_b64 vcc, exec, s[42:43]
	v_mov_b32_e32 v86, 0
	v_mov_b32_e32 v87, 0
	v_mov_b32_e32 v88, 0
	v_mov_b32_e32 v89, 0
	s_cbranch_vccnz .LBB0_704
	global_load_dwordx4 v[86:89], v[70:71], off offset:256 sc0 sc1
.LBB0_704:
	v_add_u32_e32 v70, 0x90, v188
	v_mov_b64_e32 v[68:69], s[4:5]
	v_mad_i64_i32 v[68:69], s[8:9], v70, s33, v[68:69]
	v_lshl_add_u64 v[68:69], v[2:3], 1, v[68:69]
	global_load_dwordx4 v[82:85], v[68:69], off
	v_ashrrev_i32_e32 v71, 31, v70
	v_lshlrev_b64 v[70:71], 11, v[70:71]
	v_lshl_add_u64 v[98:99], s[12:13], 0, v[70:71]
	s_and_b64 vcc, exec, s[42:43]
	v_lshl_add_u64 v[106:107], v[2:3], 1, v[98:99]
	v_mov_b32_e32 v79, 0
	v_mov_b32_e32 v80, 0
	v_mov_b32_e32 v81, 0
	s_cbranch_vccnz .LBB0_706
	global_load_dwordx4 v[78:81], v[106:107], off sc0 sc1
.LBB0_706:
	global_load_dwordx4 v[74:77], v[68:69], off offset:256
	v_mov_b32_e32 v68, 0
	s_and_b64 vcc, exec, s[42:43]
	v_mov_b32_e32 v70, 0
	v_mov_b32_e32 v71, 0
	v_mov_b32_e32 v72, 0
	v_mov_b32_e32 v73, 0
	s_cbranch_vccnz .LBB0_708
	global_load_dwordx4 v[70:73], v[106:107], off offset:256 sc0 sc1
.LBB0_708:
	s_waitcnt vmcnt(3)
	v_lshlrev_b32_e32 v0, 16, v94
	v_mul_f32_e32 v0, 0xbfb8aa3b, v0
	v_exp_f32_e32 v0, v0
	v_lshlrev_b32_e32 v69, 16, v100
	s_and_b64 vcc, exec, s[42:43]
	v_add_f32_e32 v0, 1.0, v0
	v_rcp_f32_e32 v0, v0
	s_nop 0
	v_fmac_f32_e32 v69, v64, v0
	v_and_b32_e32 v0, 0xffff0000, v94
	v_mul_f32_e32 v0, 0xbfb8aa3b, v0
	v_exp_f32_e32 v0, v0
	v_and_b32_e32 v64, 0xffff0000, v100
	v_and_b32_e32 v94, 0xffff0000, v102
	v_add_f32_e32 v0, 1.0, v0
	v_rcp_f32_e32 v0, v0
	s_nop 0
	v_fmac_f32_e32 v64, v65, v0
	v_lshlrev_b32_e32 v0, 16, v95
	v_mul_f32_e32 v0, 0xbfb8aa3b, v0
	v_exp_f32_e32 v0, v0
	v_lshlrev_b32_e32 v65, 16, v101
	v_add_f32_e32 v0, 1.0, v0
	v_rcp_f32_e32 v0, v0
	s_nop 0
	v_fmac_f32_e32 v65, v66, v0
	v_and_b32_e32 v0, 0xffff0000, v95
	v_mul_f32_e32 v0, 0xbfb8aa3b, v0
	v_exp_f32_e32 v0, v0
	v_and_b32_e32 v66, 0xffff0000, v101
	v_lshlrev_b32_e32 v95, 16, v103
	v_add_f32_e32 v0, 1.0, v0
	v_rcp_f32_e32 v0, v0
	s_nop 0
	v_fmac_f32_e32 v66, v67, v0
	v_lshlrev_b32_e32 v0, 16, v96
	v_mul_f32_e32 v0, 0xbfb8aa3b, v0
	v_exp_f32_e32 v0, v0
	v_lshlrev_b32_e32 v67, 16, v102
	v_add_f32_e32 v0, 1.0, v0
	v_rcp_f32_e32 v0, v0
	s_nop 0
	v_fmac_f32_e32 v67, v60, v0
	v_and_b32_e32 v0, 0xffff0000, v96
	v_mul_f32_e32 v0, 0xbfb8aa3b, v0
	v_exp_f32_e32 v0, v0
	v_and_b32_e32 v96, 0xffff0000, v103
	v_cvt_pk_bf16_f32 v60, v69, v64
	v_mov_b32_e32 v69, 0
	v_add_f32_e32 v0, 1.0, v0
	v_rcp_f32_e32 v0, v0
	s_nop 0
	v_fmac_f32_e32 v94, v61, v0
	v_lshlrev_b32_e32 v0, 16, v97
	v_mul_f32_e32 v0, 0xbfb8aa3b, v0
	v_exp_f32_e32 v0, v0
	v_cvt_pk_bf16_f32 v61, v65, v66
	v_lshl_add_u64 v[64:65], v[104:105], 0, v[158:159]
	v_add_f32_e32 v0, 1.0, v0
	v_rcp_f32_e32 v0, v0
	s_nop 0
	v_fmac_f32_e32 v95, v62, v0
	v_and_b32_e32 v0, 0xffff0000, v97
	v_mul_f32_e32 v0, 0xbfb8aa3b, v0
	v_exp_f32_e32 v0, v0
	v_cvt_pk_bf16_f32 v62, v67, v94
	s_nop 0
	v_add_f32_e32 v0, 1.0, v0
	v_rcp_f32_e32 v0, v0
	s_nop 0
	v_fmac_f32_e32 v96, v63, v0
	s_waitcnt vmcnt(2)
; __device__ __forceinline__ unsigned pk2(float lo, float hi) { unsigned r; asm("v_cvt_pk_bf16_f32 %0, %1, %2" : "=v"(r) : "v"(lo), "v"(hi)); return r; }
; __device__ __forceinline__ float bflo(unsigned w) { return __uint_as_float(w << 16); }
; __device__ __forceinline__ float bfhi(unsigned w) { return __uint_as_float(w & 0xffff0000u); }
; __device__ __forceinline__ float sigmoidf_(float x) { return __builtin_amdgcn_rcpf(1.f + __expf(-x)); }
;     __device__ __forceinline__ void operator()(const f32x4 (&acc)[2][2][4][2], const Unit& u, int wr, int wc, int fr, int fq) const {
;     ...
;             for (int mm = 0; mm < 2; ++mm) { const int row = row0 + ai * HALF + (2 * mp + mm) * 16;
; #pragma unroll
;                 for (int bj = 0; bj < 2; ++bj) { const int col = col0 + bj * HALF;
;                     gw[mm][bj] = *(const u32x4*)(proj + (size_t)row * PN + gbase + col);
;                     pw[mm][bj] = u.part == 1 ? *(const u32x4*)(mix + (size_t)row * DM + col) : (u32x4){0u, 0u, 0u, 0u}; } }
; #pragma unroll
;             for (int mm = 0; mm < 2; ++mm) { const int m = 2 * mp + mm; const int row = row0 + ai * HALF + m * 16;
; #pragma unroll
;                 for (int bj = 0; bj < 2; ++bj) { const int col = col0 + bj * HALF;
;                     const u32x4 g = gw[mm][bj], p = pw[mm][bj];
;                     const f32x4 v0 = acc[ai][bj][m][0], v1 = acc[ai][bj][m][1];
;                     float r[8];
;                     r[0] = sigmoidf_(bflo(g.x)) * v0[0] + bflo(p.x); r[1] = sigmoidf_(bfhi(g.x)) * v0[1] + bfhi(p.x); r[2] = sigmoidf_(bflo(g.y)) * v0[2] + bflo(p.y); r[3] = sigmoidf_(bfhi(g.y)) * v0[3] + bfhi(p.y);
;                     r[4] = sigmoidf_(bflo(g.z)) * v1[0] + bflo(p.z); r[5] = sigmoidf_(bfhi(g.z)) * v1[1] + bfhi(p.z); r[6] = sigmoidf_(bflo(g.w)) * v1[2] + bflo(p.w); r[7] = sigmoidf_(bfhi(g.w)) * v1[3] + bfhi(p.w);
;                     u32x4 w; w.x = pk2(r[0], r[1]); w.y = pk2(r[2], r[3]); w.z = pk2(r[4], r[5]); w.w = pk2(r[6], r[7]);
;                     *(u32x4*)(mix + (size_t)row * DM + col) = w; } }
	v_lshlrev_b32_e32 v0, 16, v90
	v_mul_f32_e32 v0, 0xbfb8aa3b, v0
	v_exp_f32_e32 v0, v0
	v_cvt_pk_bf16_f32 v63, v95, v96
	global_store_dwordx4 v[64:65], v[60:63], off sc0 sc1
	v_add_f32_e32 v0, 1.0, v0
	v_rcp_f32_e32 v0, v0
	v_lshlrev_b32_e32 v60, 16, v86
	v_and_b32_e32 v61, 0xffff0000, v88
	v_lshlrev_b32_e32 v62, 16, v89
	v_fmac_f32_e32 v60, v56, v0
	v_and_b32_e32 v0, 0xffff0000, v90
	v_mul_f32_e32 v0, 0xbfb8aa3b, v0
	v_exp_f32_e32 v0, v0
	v_and_b32_e32 v56, 0xffff0000, v86
	v_and_b32_e32 v63, 0xffff0000, v89
	v_add_f32_e32 v0, 1.0, v0
	v_rcp_f32_e32 v0, v0
	s_nop 0
	v_fmac_f32_e32 v56, v57, v0
	v_lshlrev_b32_e32 v0, 16, v91
	v_mul_f32_e32 v0, 0xbfb8aa3b, v0
	v_exp_f32_e32 v0, v0
	v_lshlrev_b32_e32 v57, 16, v87
	v_add_f32_e32 v0, 1.0, v0
	v_rcp_f32_e32 v0, v0
	s_nop 0
	v_fmac_f32_e32 v57, v58, v0
	v_and_b32_e32 v0, 0xffff0000, v91
	v_mul_f32_e32 v0, 0xbfb8aa3b, v0
	v_exp_f32_e32 v0, v0
	v_and_b32_e32 v58, 0xffff0000, v87
	v_add_f32_e32 v0, 1.0, v0
	v_rcp_f32_e32 v0, v0
	s_nop 0
	v_fmac_f32_e32 v58, v59, v0
	v_lshlrev_b32_e32 v0, 16, v92
	v_mul_f32_e32 v0, 0xbfb8aa3b, v0
	v_exp_f32_e32 v0, v0
	v_lshlrev_b32_e32 v59, 16, v88
	v_add_f32_e32 v0, 1.0, v0
	v_rcp_f32_e32 v0, v0
	s_nop 0
	v_fmac_f32_e32 v59, v52, v0
	v_and_b32_e32 v0, 0xffff0000, v92
	v_mul_f32_e32 v0, 0xbfb8aa3b, v0
	v_exp_f32_e32 v0, v0
	v_cvt_pk_bf16_f32 v52, v60, v56
	s_nop 0
	v_add_f32_e32 v0, 1.0, v0
	v_rcp_f32_e32 v0, v0
	s_nop 0
	v_fmac_f32_e32 v61, v53, v0
	v_lshlrev_b32_e32 v0, 16, v93
	v_mul_f32_e32 v0, 0xbfb8aa3b, v0
	v_exp_f32_e32 v0, v0
	v_cvt_pk_bf16_f32 v53, v57, v58
	s_nop 0
	v_add_f32_e32 v0, 1.0, v0
	v_rcp_f32_e32 v0, v0
	s_nop 0
	v_fmac_f32_e32 v62, v54, v0
	v_and_b32_e32 v0, 0xffff0000, v93
	v_mul_f32_e32 v0, 0xbfb8aa3b, v0
	v_exp_f32_e32 v0, v0
	v_cvt_pk_bf16_f32 v54, v59, v61
	s_nop 0
	v_add_f32_e32 v0, 1.0, v0
	v_rcp_f32_e32 v0, v0
	s_nop 0
	v_fmac_f32_e32 v63, v55, v0
	s_waitcnt vmcnt(2)
	v_lshlrev_b32_e32 v0, 16, v82
	v_mul_f32_e32 v0, 0xbfb8aa3b, v0
	v_exp_f32_e32 v0, v0
	v_cvt_pk_bf16_f32 v55, v62, v63
	global_store_dwordx4 v[64:65], v[52:55], off offset:256 sc0 sc1
	v_add_f32_e32 v0, 1.0, v0
	v_rcp_f32_e32 v0, v0
	v_lshlrev_b32_e32 v52, 16, v78
	v_and_b32_e32 v53, 0xffff0000, v80
	v_lshlrev_b32_e32 v54, 16, v81
	v_fmac_f32_e32 v52, v48, v0
	v_and_b32_e32 v0, 0xffff0000, v82
	v_mul_f32_e32 v0, 0xbfb8aa3b, v0
	v_exp_f32_e32 v0, v0
	v_and_b32_e32 v48, 0xffff0000, v78
	v_and_b32_e32 v55, 0xffff0000, v81
	v_add_f32_e32 v0, 1.0, v0
	v_rcp_f32_e32 v0, v0
	s_nop 0
	v_fmac_f32_e32 v48, v49, v0
	v_lshlrev_b32_e32 v0, 16, v83
	v_mul_f32_e32 v0, 0xbfb8aa3b, v0
	v_exp_f32_e32 v0, v0
	v_lshlrev_b32_e32 v49, 16, v79
	v_add_f32_e32 v0, 1.0, v0
	v_rcp_f32_e32 v0, v0
	s_nop 0
	v_fmac_f32_e32 v49, v50, v0
	v_and_b32_e32 v0, 0xffff0000, v83
	v_mul_f32_e32 v0, 0xbfb8aa3b, v0
	v_exp_f32_e32 v0, v0
	v_and_b32_e32 v50, 0xffff0000, v79
	v_add_f32_e32 v0, 1.0, v0
	v_rcp_f32_e32 v0, v0
	s_nop 0
	v_fmac_f32_e32 v50, v51, v0
	v_lshlrev_b32_e32 v0, 16, v84
	v_mul_f32_e32 v0, 0xbfb8aa3b, v0
	v_exp_f32_e32 v0, v0
	v_lshlrev_b32_e32 v51, 16, v80
	v_add_f32_e32 v0, 1.0, v0
	v_rcp_f32_e32 v0, v0
	s_nop 0
	v_fmac_f32_e32 v51, v44, v0
	v_and_b32_e32 v0, 0xffff0000, v84
	v_mul_f32_e32 v0, 0xbfb8aa3b, v0
	v_exp_f32_e32 v0, v0
	v_cvt_pk_bf16_f32 v44, v52, v48
	s_nop 0
	v_add_f32_e32 v0, 1.0, v0
	v_rcp_f32_e32 v0, v0
	s_nop 0
	v_fmac_f32_e32 v53, v45, v0
	v_lshlrev_b32_e32 v0, 16, v85
	v_mul_f32_e32 v0, 0xbfb8aa3b, v0
	v_exp_f32_e32 v0, v0
	v_cvt_pk_bf16_f32 v45, v49, v50
	v_lshl_add_u64 v[48:49], v[98:99], 0, v[158:159]
	v_add_f32_e32 v0, 1.0, v0
	v_rcp_f32_e32 v0, v0
	s_nop 0
	v_fmac_f32_e32 v54, v46, v0
	v_and_b32_e32 v0, 0xffff0000, v85
	v_mul_f32_e32 v0, 0xbfb8aa3b, v0
	v_exp_f32_e32 v0, v0
	v_cvt_pk_bf16_f32 v46, v51, v53
	s_nop 0
	v_add_f32_e32 v0, 1.0, v0
	v_rcp_f32_e32 v0, v0
	s_nop 0
	v_fmac_f32_e32 v55, v47, v0
	s_waitcnt vmcnt(2)
	v_lshlrev_b32_e32 v0, 16, v74
	v_mul_f32_e32 v0, 0xbfb8aa3b, v0
	v_exp_f32_e32 v0, v0
	v_cvt_pk_bf16_f32 v47, v54, v55
	global_store_dwordx4 v[48:49], v[44:47], off sc0 sc1
	v_add_f32_e32 v0, 1.0, v0
	v_rcp_f32_e32 v0, v0
	v_lshlrev_b32_e32 v44, 16, v70
	v_and_b32_e32 v45, 0xffff0000, v72
	v_lshlrev_b32_e32 v46, 16, v73
	v_fmac_f32_e32 v44, v40, v0
	v_and_b32_e32 v0, 0xffff0000, v74
	v_mul_f32_e32 v0, 0xbfb8aa3b, v0
	v_exp_f32_e32 v0, v0
	v_and_b32_e32 v40, 0xffff0000, v70
	v_and_b32_e32 v47, 0xffff0000, v73
	v_mov_b32_e32 v70, 0
	v_add_f32_e32 v0, 1.0, v0
	v_rcp_f32_e32 v0, v0
	s_nop 0
	v_fmac_f32_e32 v40, v41, v0
	v_lshlrev_b32_e32 v0, 16, v75
	v_mul_f32_e32 v0, 0xbfb8aa3b, v0
	v_exp_f32_e32 v0, v0
	v_lshlrev_b32_e32 v41, 16, v71
	v_add_f32_e32 v0, 1.0, v0
	v_rcp_f32_e32 v0, v0
	s_nop 0
	v_fmac_f32_e32 v41, v42, v0
	v_and_b32_e32 v0, 0xffff0000, v75
	v_mul_f32_e32 v0, 0xbfb8aa3b, v0
	v_exp_f32_e32 v0, v0
	v_and_b32_e32 v42, 0xffff0000, v71
	v_mov_b32_e32 v71, 0
	v_add_f32_e32 v0, 1.0, v0
	v_rcp_f32_e32 v0, v0
	s_nop 0
	v_fmac_f32_e32 v42, v43, v0
	v_lshlrev_b32_e32 v0, 16, v76
	v_mul_f32_e32 v0, 0xbfb8aa3b, v0
	v_exp_f32_e32 v0, v0
	v_lshlrev_b32_e32 v43, 16, v72
	v_add_f32_e32 v0, 1.0, v0
	v_rcp_f32_e32 v0, v0
	s_nop 0
	v_fmac_f32_e32 v43, v36, v0
	v_and_b32_e32 v0, 0xffff0000, v76
	v_mul_f32_e32 v0, 0xbfb8aa3b, v0
	v_exp_f32_e32 v0, v0
	v_cvt_pk_bf16_f32 v36, v44, v40
	s_nop 0
	v_add_f32_e32 v0, 1.0, v0
	v_rcp_f32_e32 v0, v0
	s_nop 0
	v_fmac_f32_e32 v45, v37, v0
	v_lshlrev_b32_e32 v0, 16, v77
	v_mul_f32_e32 v0, 0xbfb8aa3b, v0
	v_exp_f32_e32 v0, v0
	v_cvt_pk_bf16_f32 v37, v41, v42
	s_nop 0
	v_add_f32_e32 v0, 1.0, v0
	v_rcp_f32_e32 v0, v0
	s_nop 0
	v_fmac_f32_e32 v46, v38, v0
	v_and_b32_e32 v0, 0xffff0000, v77
	v_mul_f32_e32 v0, 0xbfb8aa3b, v0
	v_exp_f32_e32 v0, v0
	v_cvt_pk_bf16_f32 v38, v43, v45
	s_nop 0
	v_add_f32_e32 v0, 1.0, v0
	v_rcp_f32_e32 v0, v0
	s_nop 0
	v_fmac_f32_e32 v47, v39, v0
	v_cvt_pk_bf16_f32 v39, v46, v47
	global_store_dwordx4 v[48:49], v[36:39], off offset:256 sc0 sc1
	s_nop 1
	v_add_u32_e32 v36, 0xa0, v188
	v_ashrrev_i32_e32 v37, 31, v36
	v_mov_b64_e32 v[38:39], s[4:5]
	v_mad_i64_i32 v[38:39], s[8:9], v36, s33, v[38:39]
	v_lshlrev_b64 v[36:37], 11, v[36:37]
	v_lshl_add_u64 v[66:67], s[12:13], 0, v[36:37]
	v_lshl_add_u64 v[36:37], v[38:39], 0, v[158:159]
	global_load_dwordx4 v[60:63], v[36:37], off
	v_lshl_add_u64 v[38:39], v[2:3], 1, v[66:67]
	s_cbranch_vccnz .LBB0_710
	global_load_dwordx4 v[68:71], v[38:39], off sc0 sc1
; __device__ __forceinline__ unsigned pk2(float lo, float hi) { unsigned r; asm("v_cvt_pk_bf16_f32 %0, %1, %2" : "=v"(r) : "v"(lo), "v"(hi)); return r; }
; __device__ __forceinline__ float bflo(unsigned w) { return __uint_as_float(w << 16); }
; __device__ __forceinline__ float bfhi(unsigned w) { return __uint_as_float(w & 0xffff0000u); }
; __device__ __forceinline__ float sigmoidf_(float x) { return __builtin_amdgcn_rcpf(1.f + __expf(-x)); }
;     __device__ __forceinline__ void operator()(const f32x4 (&acc)[2][2][4][2], const Unit& u, int wr, int wc, int fr, int fq) const {
;     ...
;             for (int mm = 0; mm < 2; ++mm) { const int row = row0 + ai * HALF + (2 * mp + mm) * 16;
; #pragma unroll
;                 for (int bj = 0; bj < 2; ++bj) { const int col = col0 + bj * HALF;
;                     gw[mm][bj] = *(const u32x4*)(proj + (size_t)row * PN + gbase + col);
;                     pw[mm][bj] = u.part == 1 ? *(const u32x4*)(mix + (size_t)row * DM + col) : (u32x4){0u, 0u, 0u, 0u}; } }
; #pragma unroll
;             for (int mm = 0; mm < 2; ++mm) { const int m = 2 * mp + mm; const int row = row0 + ai * HALF + m * 16;
; #pragma unroll
;                 for (int bj = 0; bj < 2; ++bj) { const int col = col0 + bj * HALF;
;                     const u32x4 g = gw[mm][bj], p = pw[mm][bj];
;                     const f32x4 v0 = acc[ai][bj][m][0], v1 = acc[ai][bj][m][1];
;                     float r[8];
;                     r[0] = sigmoidf_(bflo(g.x)) * v0[0] + bflo(p.x); r[1] = sigmoidf_(bfhi(g.x)) * v0[1] + bfhi(p.x); r[2] = sigmoidf_(bflo(g.y)) * v0[2] + bflo(p.y); r[3] = sigmoidf_(bfhi(g.y)) * v0[3] + bfhi(p.y);
;                     r[4] = sigmoidf_(bflo(g.z)) * v1[0] + bflo(p.z); r[5] = sigmoidf_(bfhi(g.z)) * v1[1] + bfhi(p.z); r[6] = sigmoidf_(bflo(g.w)) * v1[2] + bflo(p.w); r[7] = sigmoidf_(bfhi(g.w)) * v1[3] + bfhi(p.w);
;                     u32x4 w; w.x = pk2(r[0], r[1]); w.y = pk2(r[2], r[3]); w.z = pk2(r[4], r[5]); w.w = pk2(r[6], r[7]);
;                     *(u32x4*)(mix + (size_t)row * DM + col) = w; } }
.LBB0_710:
	global_load_dwordx4 v[56:59], v[36:37], off offset:256
	v_mov_b32_e32 v44, 0
	s_and_b64 vcc, exec, s[42:43]
	v_mov_b32_e32 v52, 0
	v_mov_b32_e32 v53, 0
	v_mov_b32_e32 v54, 0
	v_mov_b32_e32 v55, 0
	s_cbranch_vccnz .LBB0_712
	global_load_dwordx4 v[52:55], v[38:39], off offset:256 sc0 sc1
.LBB0_712:
	v_add_u32_e32 v38, 0xb0, v188
	v_mov_b64_e32 v[36:37], s[4:5]
	v_mad_i64_i32 v[36:37], s[4:5], v38, s33, v[36:37]
	v_lshl_add_u64 v[36:37], v[2:3], 1, v[36:37]
	global_load_dwordx4 v[48:51], v[36:37], off
	v_ashrrev_i32_e32 v39, 31, v38
	v_lshlrev_b64 v[38:39], 11, v[38:39]
	v_lshl_add_u64 v[64:65], s[12:13], 0, v[38:39]
	s_and_b64 vcc, exec, s[42:43]
	v_lshl_add_u64 v[2:3], v[2:3], 1, v[64:65]
	v_mov_b32_e32 v45, 0
	v_mov_b32_e32 v46, 0
	v_mov_b32_e32 v47, 0
	s_cbranch_vccnz .LBB0_714
	global_load_dwordx4 v[44:47], v[2:3], off sc0 sc1
.LBB0_714:
	global_load_dwordx4 v[40:43], v[36:37], off offset:256
	v_mov_b32_e32 v36, 0
	s_and_b64 vcc, exec, s[42:43]
	v_mov_b32_e32 v37, 0
	v_mov_b32_e32 v38, 0
	v_mov_b32_e32 v39, 0
	s_cbranch_vccnz .LBB0_716
	global_load_dwordx4 v[36:39], v[2:3], off offset:256 sc0 sc1
.LBB0_716:
	s_waitcnt vmcnt(3)
	v_lshlrev_b32_e32 v0, 16, v60
	v_mul_f32_e32 v0, 0xbfb8aa3b, v0
	v_exp_f32_e32 v0, v0
	v_and_b32_e32 v3, 0xffff0000, v60
	v_mul_f32_e32 v3, 0xbfb8aa3b, v3
	v_lshlrev_b32_e32 v60, 16, v61
	v_add_f32_e32 v0, 1.0, v0
	v_rcp_f32_e32 v0, v0
	v_exp_f32_e32 v3, v3
	v_mul_f32_e32 v60, 0xbfb8aa3b, v60
	v_exp_f32_e32 v60, v60
	v_lshlrev_b32_e32 v2, 16, v68
	v_fmac_f32_e32 v2, v32, v0
	v_add_f32_e32 v0, 1.0, v3
	v_rcp_f32_e32 v0, v0
	v_add_f32_e32 v3, 1.0, v60
	v_rcp_f32_e32 v3, v3
	v_and_b32_e32 v32, 0xffff0000, v68
	v_fmac_f32_e32 v32, v33, v0
	v_lshlrev_b32_e32 v0, 16, v69
	v_fmac_f32_e32 v0, v34, v3
	v_and_b32_e32 v3, 0xffff0000, v61
	v_mul_f32_e32 v3, 0xbfb8aa3b, v3
	v_lshlrev_b32_e32 v33, 16, v62
	v_exp_f32_e32 v3, v3
	v_mul_f32_e32 v33, 0xbfb8aa3b, v33
	v_exp_f32_e32 v33, v33
	v_and_b32_e32 v60, 0xffff0000, v62
	v_add_f32_e32 v3, 1.0, v3
	v_rcp_f32_e32 v3, v3
	v_add_f32_e32 v33, 1.0, v33
	v_mul_f32_e32 v60, 0xbfb8aa3b, v60
	v_rcp_f32_e32 v33, v33
	v_exp_f32_e32 v60, v60
	v_and_b32_e32 v34, 0xffff0000, v69
	v_fmac_f32_e32 v34, v35, v3
	v_lshlrev_b32_e32 v3, 16, v70
	v_fmac_f32_e32 v3, v28, v33
	v_add_f32_e32 v28, 1.0, v60
	v_and_b32_e32 v60, 0xffff0000, v63
	v_mul_f32_e32 v60, 0xbfb8aa3b, v60
	v_rcp_f32_e32 v28, v28
	v_exp_f32_e32 v60, v60
	v_lshlrev_b32_e32 v35, 16, v63
	v_and_b32_e32 v33, 0xffff0000, v70
	v_mul_f32_e32 v35, 0xbfb8aa3b, v35
	v_exp_f32_e32 v35, v35
	v_fmac_f32_e32 v33, v29, v28
	v_add_f32_e32 v29, 1.0, v60
	v_rcp_f32_e32 v29, v29
	v_add_f32_e32 v28, 1.0, v35
	v_and_b32_e32 v60, 0xffff0000, v71
	v_rcp_f32_e32 v28, v28
	v_fmac_f32_e32 v60, v31, v29
	v_cvt_pk_bf16_f32 v29, v0, v34
	s_waitcnt vmcnt(2)
	v_lshlrev_b32_e32 v0, 16, v56
	v_mul_f32_e32 v0, 0xbfb8aa3b, v0
	v_exp_f32_e32 v0, v0
	v_lshlrev_b32_e32 v35, 16, v71
	v_fmac_f32_e32 v35, v30, v28
	v_cvt_pk_bf16_f32 v28, v2, v32
	v_cvt_pk_bf16_f32 v30, v3, v33
	v_lshl_add_u64 v[2:3], v[66:67], 0, v[158:159]
	v_cvt_pk_bf16_f32 v31, v35, v60
	global_store_dwordx4 v[2:3], v[28:31], off sc0 sc1
	v_add_f32_e32 v0, 1.0, v0
	v_rcp_f32_e32 v0, v0
	v_and_b32_e32 v29, 0xffff0000, v56
	v_mul_f32_e32 v29, 0xbfb8aa3b, v29
	v_lshlrev_b32_e32 v30, 16, v57
	v_exp_f32_e32 v29, v29
	v_mul_f32_e32 v30, 0xbfb8aa3b, v30
	v_exp_f32_e32 v30, v30
	v_lshlrev_b32_e32 v28, 16, v52
	v_fmac_f32_e32 v28, v24, v0
	v_add_f32_e32 v0, 1.0, v29
	v_rcp_f32_e32 v0, v0
	v_add_f32_e32 v24, 1.0, v30
	v_rcp_f32_e32 v24, v24
	v_and_b32_e32 v29, 0xffff0000, v52
	v_fmac_f32_e32 v29, v25, v0
	v_lshlrev_b32_e32 v0, 16, v53
	v_fmac_f32_e32 v0, v26, v24
	v_and_b32_e32 v24, 0xffff0000, v57
	v_mul_f32_e32 v24, 0xbfb8aa3b, v24
	v_lshlrev_b32_e32 v25, 16, v58
	v_exp_f32_e32 v24, v24
	v_mul_f32_e32 v25, 0xbfb8aa3b, v25
	v_exp_f32_e32 v25, v25
	v_and_b32_e32 v30, 0xffff0000, v58
	v_add_f32_e32 v24, 1.0, v24
	v_rcp_f32_e32 v24, v24
	v_add_f32_e32 v25, 1.0, v25
	v_mul_f32_e32 v30, 0xbfb8aa3b, v30
	v_rcp_f32_e32 v25, v25
	v_exp_f32_e32 v30, v30
	v_and_b32_e32 v26, 0xffff0000, v53
	v_fmac_f32_e32 v26, v27, v24
	v_lshlrev_b32_e32 v24, 16, v54
	v_fmac_f32_e32 v24, v20, v25
	v_add_f32_e32 v20, 1.0, v30
	v_and_b32_e32 v30, 0xffff0000, v59
	v_mul_f32_e32 v30, 0xbfb8aa3b, v30
	v_rcp_f32_e32 v20, v20
	v_exp_f32_e32 v30, v30
	v_and_b32_e32 v25, 0xffff0000, v54
	v_lshlrev_b32_e32 v27, 16, v59
	v_mul_f32_e32 v27, 0xbfb8aa3b, v27
	v_fmac_f32_e32 v25, v21, v20
	v_add_f32_e32 v21, 1.0, v30
	v_exp_f32_e32 v27, v27
	v_rcp_f32_e32 v21, v21
	v_and_b32_e32 v30, 0xffff0000, v55
	s_and_b64 vcc, exec, s[40:41]
	v_add_f32_e32 v20, 1.0, v27
	v_fmac_f32_e32 v30, v23, v21
	v_cvt_pk_bf16_f32 v21, v0, v26
	s_waitcnt vmcnt(2)
; __device__ __forceinline__ unsigned pk2(float lo, float hi) { unsigned r; asm("v_cvt_pk_bf16_f32 %0, %1, %2" : "=v"(r) : "v"(lo), "v"(hi)); return r; }
; __device__ __forceinline__ float bflo(unsigned w) { return __uint_as_float(w << 16); }
; __device__ __forceinline__ float bfhi(unsigned w) { return __uint_as_float(w & 0xffff0000u); }
; __device__ __forceinline__ float sigmoidf_(float x) { return __builtin_amdgcn_rcpf(1.f + __expf(-x)); }
;     __device__ __forceinline__ void operator()(const f32x4 (&acc)[2][2][4][2], const Unit& u, int wr, int wc, int fr, int fq) const {
;     ...
;             for (int mm = 0; mm < 2; ++mm) { const int m = 2 * mp + mm; const int row = row0 + ai * HALF + m * 16;
; #pragma unroll
;                 for (int bj = 0; bj < 2; ++bj) { const int col = col0 + bj * HALF;
;                     const u32x4 g = gw[mm][bj], p = pw[mm][bj];
;                     const f32x4 v0 = acc[ai][bj][m][0], v1 = acc[ai][bj][m][1];
;                     float r[8];
;                     r[0] = sigmoidf_(bflo(g.x)) * v0[0] + bflo(p.x); r[1] = sigmoidf_(bfhi(g.x)) * v0[1] + bfhi(p.x); r[2] = sigmoidf_(bflo(g.y)) * v0[2] + bflo(p.y); r[3] = sigmoidf_(bfhi(g.y)) * v0[3] + bfhi(p.y);
;                     r[4] = sigmoidf_(bflo(g.z)) * v1[0] + bflo(p.z); r[5] = sigmoidf_(bfhi(g.z)) * v1[1] + bfhi(p.z); r[6] = sigmoidf_(bflo(g.w)) * v1[2] + bflo(p.w); r[7] = sigmoidf_(bfhi(g.w)) * v1[3] + bfhi(p.w);
;                     u32x4 w; w.x = pk2(r[0], r[1]); w.y = pk2(r[2], r[3]); w.z = pk2(r[4], r[5]); w.w = pk2(r[6], r[7]);
;                     *(u32x4*)(mix + (size_t)row * DM + col) = w; } }
	v_lshlrev_b32_e32 v0, 16, v48
	v_rcp_f32_e32 v20, v20
	v_mul_f32_e32 v0, 0xbfb8aa3b, v0
	v_exp_f32_e32 v0, v0
	v_lshlrev_b32_e32 v27, 16, v55
	v_fmac_f32_e32 v27, v22, v20
	v_cvt_pk_bf16_f32 v20, v28, v29
	v_cvt_pk_bf16_f32 v22, v24, v25
	v_cvt_pk_bf16_f32 v23, v27, v30
	global_store_dwordx4 v[2:3], v[20:23], off offset:256 sc0 sc1
	v_and_b32_e32 v3, 0xffff0000, v48
	v_add_f32_e32 v0, 1.0, v0
	v_mul_f32_e32 v3, 0xbfb8aa3b, v3
	v_lshlrev_b32_e32 v20, 16, v49
	v_rcp_f32_e32 v0, v0
	v_exp_f32_e32 v3, v3
	v_mul_f32_e32 v20, 0xbfb8aa3b, v20
	v_exp_f32_e32 v20, v20
	v_lshlrev_b32_e32 v2, 16, v44
	v_fmac_f32_e32 v2, v16, v0
	v_add_f32_e32 v0, 1.0, v3
	v_rcp_f32_e32 v0, v0
	v_add_f32_e32 v3, 1.0, v20
	v_rcp_f32_e32 v3, v3
	v_and_b32_e32 v16, 0xffff0000, v44
	v_fmac_f32_e32 v16, v17, v0
	v_lshlrev_b32_e32 v0, 16, v45
	v_fmac_f32_e32 v0, v18, v3
	v_and_b32_e32 v3, 0xffff0000, v49
	v_mul_f32_e32 v3, 0xbfb8aa3b, v3
	v_lshlrev_b32_e32 v17, 16, v50
	v_exp_f32_e32 v3, v3
	v_mul_f32_e32 v17, 0xbfb8aa3b, v17
	v_exp_f32_e32 v17, v17
	v_and_b32_e32 v20, 0xffff0000, v50
	v_add_f32_e32 v3, 1.0, v3
	v_rcp_f32_e32 v3, v3
	v_add_f32_e32 v17, 1.0, v17
	v_mul_f32_e32 v20, 0xbfb8aa3b, v20
	v_rcp_f32_e32 v17, v17
	v_exp_f32_e32 v20, v20
	v_and_b32_e32 v18, 0xffff0000, v45
	v_fmac_f32_e32 v18, v19, v3
	v_lshlrev_b32_e32 v3, 16, v46
	v_fmac_f32_e32 v3, v12, v17
	v_add_f32_e32 v12, 1.0, v20
	v_and_b32_e32 v20, 0xffff0000, v51
	v_mul_f32_e32 v20, 0xbfb8aa3b, v20
	v_rcp_f32_e32 v12, v12
	v_exp_f32_e32 v20, v20
	v_and_b32_e32 v17, 0xffff0000, v46
	v_lshlrev_b32_e32 v19, 16, v51
	v_mul_f32_e32 v19, 0xbfb8aa3b, v19
	v_fmac_f32_e32 v17, v13, v12
	v_add_f32_e32 v13, 1.0, v20
	v_exp_f32_e32 v19, v19
	v_rcp_f32_e32 v13, v13
	v_and_b32_e32 v20, 0xffff0000, v47
	s_mov_b64 s[4:5], -1
	v_add_f32_e32 v12, 1.0, v19
	v_fmac_f32_e32 v20, v15, v13
	v_cvt_pk_bf16_f32 v13, v0, v18
	s_waitcnt vmcnt(2)
	v_lshlrev_b32_e32 v0, 16, v40
	v_rcp_f32_e32 v12, v12
	v_mul_f32_e32 v0, 0xbfb8aa3b, v0
	v_exp_f32_e32 v0, v0
	v_lshlrev_b32_e32 v19, 16, v47
	v_fmac_f32_e32 v19, v14, v12
	v_cvt_pk_bf16_f32 v12, v2, v16
	v_cvt_pk_bf16_f32 v14, v3, v17
	v_lshl_add_u64 v[16:17], v[64:65], 0, v[158:159]
	v_and_b32_e32 v3, 0xffff0000, v40
	v_cvt_pk_bf16_f32 v15, v19, v20
	global_store_dwordx4 v[16:17], v[12:15], off sc0 sc1
	v_add_f32_e32 v0, 1.0, v0
	v_mul_f32_e32 v3, 0xbfb8aa3b, v3
	v_lshlrev_b32_e32 v12, 16, v41
	v_rcp_f32_e32 v0, v0
	v_exp_f32_e32 v3, v3
	v_mul_f32_e32 v12, 0xbfb8aa3b, v12
	v_exp_f32_e32 v12, v12
	v_lshlrev_b32_e32 v2, 16, v36
	v_fmac_f32_e32 v2, v8, v0
	v_add_f32_e32 v0, 1.0, v3
	v_rcp_f32_e32 v0, v0
	v_add_f32_e32 v3, 1.0, v12
	v_rcp_f32_e32 v3, v3
	v_and_b32_e32 v8, 0xffff0000, v36
	v_fmac_f32_e32 v8, v9, v0
	v_lshlrev_b32_e32 v0, 16, v37
	v_fmac_f32_e32 v0, v10, v3
	v_and_b32_e32 v3, 0xffff0000, v41
	v_mul_f32_e32 v3, 0xbfb8aa3b, v3
	v_lshlrev_b32_e32 v9, 16, v42
	v_exp_f32_e32 v3, v3
	v_mul_f32_e32 v9, 0xbfb8aa3b, v9
	v_exp_f32_e32 v9, v9
	v_and_b32_e32 v12, 0xffff0000, v42
	v_add_f32_e32 v3, 1.0, v3
	v_rcp_f32_e32 v3, v3
	v_add_f32_e32 v9, 1.0, v9
	v_rcp_f32_e32 v9, v9
	v_mul_f32_e32 v12, 0xbfb8aa3b, v12
	v_exp_f32_e32 v12, v12
	v_and_b32_e32 v10, 0xffff0000, v37
	v_fmac_f32_e32 v10, v11, v3
	v_lshlrev_b32_e32 v11, 16, v38
	v_fmac_f32_e32 v11, v4, v9
	v_lshlrev_b32_e32 v9, 16, v43
	v_add_f32_e32 v3, 1.0, v12
	v_mul_f32_e32 v9, 0xbfb8aa3b, v9
	v_and_b32_e32 v12, 0xffff0000, v43
	v_rcp_f32_e32 v3, v3
	v_exp_f32_e32 v9, v9
	v_mul_f32_e32 v12, 0xbfb8aa3b, v12
	v_exp_f32_e32 v12, v12
	v_and_b32_e32 v4, 0xffff0000, v38
	v_fmac_f32_e32 v4, v5, v3
	v_add_f32_e32 v3, 1.0, v9
	v_rcp_f32_e32 v3, v3
	v_add_f32_e32 v5, 1.0, v12
	v_rcp_f32_e32 v5, v5
	v_lshlrev_b32_e32 v9, 16, v39
	v_fmac_f32_e32 v9, v6, v3
	v_and_b32_e32 v6, 0xffff0000, v39
	v_fmac_f32_e32 v6, v7, v5
	v_cvt_pk_bf16_f32 v2, v2, v8
	v_cvt_pk_bf16_f32 v3, v0, v10
	v_cvt_pk_bf16_f32 v4, v11, v4
	v_cvt_pk_bf16_f32 v5, v9, v6
	global_store_dwordx4 v[16:17], v[2:5], off offset:256 sc0 sc1
	s_cmp_eq_u32 s100, 1
	s_cbranch_scc0 .Lpp5_nf
	s_waitcnt vmcnt(0)
	s_barrier
	v_readfirstlane_b32 s8, v166
	s_nop 0
	s_cmp_lt_u32 s8, 64
	s_cbranch_scc0 .Lpp5_nf
	v_readlane_b32 s9, v252, 2
	s_lshr_b32 s9, s9, 9
	s_xor_b32 s9, s9, 1
	s_lshl_b32 s9, s9, 2
	s_addk_i32 s9, 0x3700
	v_mov_b32_e32 v120, s9
	v_mov_b32_e32 v121, 1
	s_add_u32 s20, s26, 0x1d780000
	s_addc_u32 s21, s27, 0
	global_store_dword v120, v121, s[20:21] sc0 sc1
.Lpp5_nf:
	s_cbranch_vccnz .LBB0_655
	s_andn2_b64 vcc, exec, s[6:7]
	s_cbranch_vccnz .LBB0_654
	s_barrier
	s_branch .LBB0_654
